# attention: PV V-fragment LDS reads batched into spare VGPRs with counted lgkmcnt (late waves fused PV+QK with K reads interleaved); dropped redundant vmcnt waits on Q fragments in QK ladders
# speedup vs baseline: 1.0048x; 1.0048x over previous
; #define AT_LAS __attribute__((address_space(3)))
; #define AT_WAIT_BAR(N) asm volatile("s_waitcnt vmcnt(" #N ") lgkmcnt(0)\n\ts_barrier" ::: "memory")
; __device__ __forceinline__ void qkt(f32x16& p0, f32x16& p1, AT_LAS const char* kb, const bf16x8 (&qr)[6], const f32x16& negm) {
;     bf16x8 kf[12];
; #pragma unroll
;     for (int d0 = 0; d0 < 6; ++d0) { kf[2 * d0] = *(AT_LAS const bf16x8*)(kb + d0 * 2048); kf[2 * d0 + 1] = *(AT_LAS const bf16x8*)(kb + d0 * 2048 + 512); }
;     __builtin_amdgcn_sched_barrier(0);
;     p0 = __builtin_amdgcn_mfma_f32_32x32x16_bf16(kf[0], qr[0], negm, 0, 0, 0); p1 = __builtin_amdgcn_mfma_f32_32x32x16_bf16(kf[1], qr[0], negm, 0, 0, 0);
; #pragma unroll
;     for (int d0 = 1; d0 < 6; ++d0) { p0 = __builtin_amdgcn_mfma_f32_32x32x16_bf16(kf[2 * d0], qr[d0], p0, 0, 0, 0); p1 = __builtin_amdgcn_mfma_f32_32x32x16_bf16(kf[2 * d0 + 1], qr[d0], p1, 0, 0, 0); }
;     asm volatile("s_nop 15\n\ts_nop 7" : "+v"(p0), "+v"(p1));
; }
; template <int THRL>
; __device__ __forceinline__ void attn_item(int b, int h, int s, const bf16_t* Q, const bf16_t* KN, const bf16_t* KR, const bf16_t* V, const float* goa  , bf16_t* Y, float* ssqy, AT_LAS char* shm, int wid0) {
;     ...
;         float mhat = 0.f, l_reg = 0.f; f32x16 o[2]; o[0] = f32x16{}; o[1] = f32x16{};
;         f32x16 negm = f32x16{}; asm volatile("" : "+v"(negm));
;         u32x4 pw0 = u32x4{}, pw1 = u32x4{}, pw2 = u32x4{}, pw3 = u32x4{}; bool have = false;
;         f32x16 p0 = f32x16{}, p1 = f32x16{};
;         AT_WAIT_BAR(6);
;         if (!late) qkt(p0, p1, kp0, qr, negm);
.LBB13_748:
	v_mov_b32_e32 v14, v1
	v_mov_b32_e32 v15, v1
	v_mov_b32_e32 v0, v1
	s_waitcnt lgkmcnt(0)
	v_mov_b32_e32 v2, v1
	v_mov_b32_e32 v3, v1
	v_mov_b32_e32 v4, v1
	v_mov_b32_e32 v5, v1
	v_mov_b32_e32 v6, v1
	v_mov_b32_e32 v7, v1
	v_mov_b32_e32 v8, v1
	v_mov_b32_e32 v9, v1
	v_mov_b32_e32 v10, v1
	v_mov_b32_e32 v11, v1
	v_mov_b32_e32 v12, v1
	v_mov_b32_e32 v13, v1
	v_mov_b64_e32 v[80:81], v[14:15]
	v_mov_b64_e32 v[78:79], v[12:13]
	v_mov_b64_e32 v[76:77], v[10:11]
	v_mov_b64_e32 v[74:75], v[8:9]
	v_mov_b64_e32 v[72:73], v[6:7]
	v_mov_b64_e32 v[70:71], v[4:5]
	v_mov_b64_e32 v[68:69], v[2:3]
	v_mov_b64_e32 v[66:67], v[0:1]
	s_waitcnt vmcnt(6) lgkmcnt(0)
	s_barrier
	v_cndmask_b32_e64 v16, 0, 1, s[90:91]
	v_cmp_ne_u32_e64 s[76:77], 1, v16
	s_andn2_b64 vcc, exec, s[90:91]
	s_cbranch_vccnz .LBB13_750
	ds_read_b128 v[2:5], v190
	ds_read_b128 v[6:9], v190 offset:512
	ds_read_b128 v[10:13], v190 offset:2048
	ds_read_b128 v[14:17], v190 offset:2560
	ds_read_b128 v[50:53], v190 offset:4096
	ds_read_b128 v[54:57], v190 offset:4608
	ds_read_b128 v[58:61], v190 offset:6144
	ds_read_b128 v[62:65], v190 offset:6656
	ds_read_b128 v[106:109], v190 offset:8192
	ds_read_b128 v[110:113], v190 offset:8704
	ds_read_b128 v[114:117], v190 offset:10240
	ds_read_b128 v[118:121], v190 offset:10752
	s_waitcnt lgkmcnt(11)
	v_mfma_f32_32x32x16_bf16 v[18:33], v[2:5], v[82:85], v[66:81]
	s_waitcnt lgkmcnt(10)
	v_mfma_f32_32x32x16_bf16 v[34:49], v[6:9], v[82:85], v[66:81]
	s_waitcnt lgkmcnt(9)
	v_mfma_f32_32x32x16_bf16 v[18:33], v[10:13], v[86:89], v[18:33]
	s_waitcnt lgkmcnt(8)
	v_mfma_f32_32x32x16_bf16 v[34:49], v[14:17], v[86:89], v[34:49]
	s_waitcnt lgkmcnt(7)
	v_mfma_f32_32x32x16_bf16 v[18:33], v[50:53], v[90:93], v[18:33]
	s_waitcnt lgkmcnt(6)
	v_mfma_f32_32x32x16_bf16 v[34:49], v[54:57], v[90:93], v[34:49]
	s_waitcnt lgkmcnt(5)
	v_mfma_f32_32x32x16_bf16 v[18:33], v[58:61], v[94:97], v[18:33]
	s_waitcnt lgkmcnt(4)
	v_mfma_f32_32x32x16_bf16 v[34:49], v[62:65], v[94:97], v[34:49]
	s_waitcnt lgkmcnt(3)
	v_mfma_f32_32x32x16_bf16 v[18:33], v[106:109], v[98:101], v[18:33]
	s_waitcnt lgkmcnt(2)
	v_mfma_f32_32x32x16_bf16 v[34:49], v[110:113], v[98:101], v[34:49]
	s_waitcnt lgkmcnt(1)
	v_mfma_f32_32x32x16_bf16 v[18:33], v[114:117], v[102:105], v[18:33]
	s_waitcnt lgkmcnt(0)
	v_mfma_f32_32x32x16_bf16 v[34:49], v[118:121], v[102:105], v[34:49]
	s_nop 15
	s_nop 7
	s_branch .LBB13_751

; #define AT_WAIT_BAR(N) asm volatile("s_waitcnt vmcnt(" #N ") lgkmcnt(0)\n\ts_barrier" ::: "memory")
; template <int THRL>
; __device__ __forceinline__ void attn_item(int b, int h, int s, const bf16_t* Q, const bf16_t* KN, const bf16_t* KR, const bf16_t* V, const float* goa  , bf16_t* Y, float* ssqy, AT_LAS char* shm, int wid0) {
;     ...
;         const int qb = (ui == 0) ? s : (ui == 1) ? 7 - s : (ui == 2) ? 2 + s : 5 - s; const int q0 = qb * 256;
;         const int NT = (q0 + 256) / KVBLK;
;         float mhat = 0.f, l_reg = 0.f; f32x16 o[2]; o[0] = f32x16{}; o[1] = f32x16{};
;         f32x16 negm = f32x16{}; asm volatile("" : "+v"(negm));
;         u32x4 pw0 = u32x4{}, pw1 = u32x4{}, pw2 = u32x4{}, pw3 = u32x4{}; bool have = false;
;         f32x16 p0 = f32x16{}, p1 = f32x16{};
;         AT_WAIT_BAR(6);
;         if (!late) qkt(p0, p1, kp0, qr, negm);
;         for (int t = 0; t < NT; ++t) {
;             AT_WAIT_BAR(3);
;             AT_DMA(t + 3, t + 2, NT);
;             const int jb = t - (NT - 4);
;             const bool need = jb <= wq;
;             if (late) { if (have) pv(o, vp0 + ((t - 1) & 3) * VSLOTB, pw0, pw1, pw2, pw3);
;                         have = false; if (need) qkt(p0, p1, kp0 + (t & 3) * KSLOTB, qr, negm); }
.LBB13_751:
	s_cmp_eq_u32 s8, 2
	v_readlane_b32 s3, v238, 57
	s_cselect_b32 s3, s3, s86
	s_cmp_eq_u32 s8, 1
	s_cselect_b64 s[82:83], -1, 0
	s_and_b64 s[4:5], s[82:83], exec
	v_readlane_b32 s4, v238, 59
	s_cselect_b32 s3, s4, s3
	s_cmp_eq_u32 s8, 0
	s_cselect_b64 s[94:95], -1, 0
	s_and_b64 s[4:5], s[94:95], exec
	v_readlane_b32 s4, v238, 58
	s_cselect_b32 s3, s4, s3
	s_lshl_b32 s4, s3, 8
	s_add_i32 s5, s4, 0x100
	s_lshr_b32 s79, s5, 6
	v_readlane_b32 s80, v238, 16
	v_readlane_b32 s5, v238, 52
	s_waitcnt vmcnt(3) lgkmcnt(0)
	s_barrier
	s_add_i32 s5, s5, s80
	s_mov_b32 s9, m0
	s_mov_b32 m0, s5
	s_nop 0
	global_load_lds_dwordx4 v[144:145], off
	s_mov_b32 m0, s9
	v_readlane_b32 s5, v238, 54
	s_add_i32 s5, s5, s80
	s_mov_b32 s9, m0
	s_mov_b32 m0, s5
	s_nop 0
	global_load_lds_dwordx4 v[146:147], off
	s_mov_b32 m0, s9
	s_add_i32 s9, s33, 0x10000
	s_sub_i32 s5, 4, s79
	s_cmp_le_i32 s5, s2
	s_cselect_b64 s[92:93], -1, 0
	s_and_b64 s[80:81], s[0:1], s[92:93]
	s_andn2_b64 vcc, exec, s[80:81]
	s_mov_b32 s80, m0
	s_mov_b32 m0, s9
	s_nop 0
	global_load_lds_dwordx4 v[148:149], off
	s_mov_b32 m0, s80
	s_cbranch_vccnz .LBB13_753
	ds_read_b128 v[2:5], v190
	ds_read_b128 v[6:9], v190 offset:512
	ds_read_b128 v[10:13], v190 offset:2048
	ds_read_b128 v[14:17], v190 offset:2560
	ds_read_b128 v[50:53], v190 offset:4096
	ds_read_b128 v[54:57], v190 offset:4608
	ds_read_b128 v[58:61], v190 offset:6144
	ds_read_b128 v[62:65], v190 offset:6656
	ds_read_b128 v[106:109], v190 offset:8192
	ds_read_b128 v[110:113], v190 offset:8704
	ds_read_b128 v[114:117], v190 offset:10240
	ds_read_b128 v[118:121], v190 offset:10752
	s_waitcnt lgkmcnt(11)
	v_mfma_f32_32x32x16_bf16 v[18:33], v[2:5], v[82:85], v[66:81]
	s_waitcnt lgkmcnt(10)
	v_mfma_f32_32x32x16_bf16 v[34:49], v[6:9], v[82:85], v[66:81]
	s_waitcnt lgkmcnt(9)
	v_mfma_f32_32x32x16_bf16 v[18:33], v[10:13], v[86:89], v[18:33]
	s_waitcnt lgkmcnt(8)
	v_mfma_f32_32x32x16_bf16 v[34:49], v[14:17], v[86:89], v[34:49]
	s_waitcnt lgkmcnt(7)
	v_mfma_f32_32x32x16_bf16 v[18:33], v[50:53], v[90:93], v[18:33]
	s_waitcnt lgkmcnt(6)
	v_mfma_f32_32x32x16_bf16 v[34:49], v[54:57], v[90:93], v[34:49]
	s_waitcnt lgkmcnt(5)
	v_mfma_f32_32x32x16_bf16 v[18:33], v[58:61], v[94:97], v[18:33]
	s_waitcnt lgkmcnt(4)
	v_mfma_f32_32x32x16_bf16 v[34:49], v[62:65], v[94:97], v[34:49]
	s_waitcnt lgkmcnt(3)
	v_mfma_f32_32x32x16_bf16 v[18:33], v[106:109], v[98:101], v[18:33]
	s_waitcnt lgkmcnt(2)
	v_mfma_f32_32x32x16_bf16 v[34:49], v[110:113], v[98:101], v[34:49]
	s_waitcnt lgkmcnt(1)
	v_mfma_f32_32x32x16_bf16 v[18:33], v[114:117], v[102:105], v[18:33]
	s_waitcnt lgkmcnt(0)
	v_mfma_f32_32x32x16_bf16 v[34:49], v[118:121], v[102:105], v[34:49]
	s_nop 15
	s_nop 7

; #define AT_LAS __attribute__((address_space(3)))
; __device__ __forceinline__ void qkt(f32x16& p0, f32x16& p1, AT_LAS const char* kb, const bf16x8 (&qr)[6], const f32x16& negm) {
;     bf16x8 kf[12];
; #pragma unroll
;     for (int d0 = 0; d0 < 6; ++d0) { kf[2 * d0] = *(AT_LAS const bf16x8*)(kb + d0 * 2048); kf[2 * d0 + 1] = *(AT_LAS const bf16x8*)(kb + d0 * 2048 + 512); }
;     __builtin_amdgcn_sched_barrier(0);
;     p0 = __builtin_amdgcn_mfma_f32_32x32x16_bf16(kf[0], qr[0], negm, 0, 0, 0); p1 = __builtin_amdgcn_mfma_f32_32x32x16_bf16(kf[1], qr[0], negm, 0, 0, 0);
; #pragma unroll
;     for (int d0 = 1; d0 < 6; ++d0) { p0 = __builtin_amdgcn_mfma_f32_32x32x16_bf16(kf[2 * d0], qr[d0], p0, 0, 0, 0); p1 = __builtin_amdgcn_mfma_f32_32x32x16_bf16(kf[2 * d0 + 1], qr[d0], p1, 0, 0, 0); }
;     asm volatile("s_nop 15\n\ts_nop 7" : "+v"(p0), "+v"(p1));
; }
; template <int THRL>
; __device__ __forceinline__ void attn_item(int b, int h, int s, const bf16_t* Q, const bf16_t* KN, const bf16_t* KR, const bf16_t* V, const float* goa  , bf16_t* Y, float* ssqy, AT_LAS char* shm, int wid0) {
;     ...
;             if (!late) { if (t + 1 < NT && (jb + 1) <= wq) qkt(p0, p1, kp0 + ((t + 1) & 3) * KSLOTB, qr, negm); }
.LBB13_761:
	s_cmp_ge_i32 s5, s2
	s_cselect_b64 s[80:81], -1, 0
	s_or_b64 s[80:81], s[0:1], s[80:81]
	s_andn2_b64 vcc, exec, s[80:81]
	s_cbranch_vccz .LBB13_763
	ds_read_b128 v[34:37], v190 offset:12288
	ds_read_b128 v[154:157], v190 offset:12800
	ds_read_b128 v[158:161], v190 offset:14336
	ds_read_b128 v[162:165], v190 offset:14848
	ds_read_b128 v[166:169], v190 offset:16384
	ds_read_b128 v[170:173], v190 offset:16896
	ds_read_b128 v[174:177], v190 offset:18432
	ds_read_b128 v[178:181], v190 offset:18944
	ds_read_b128 v[198:201], v190 offset:20480
	ds_read_b128 v[202:205], v190 offset:20992
	ds_read_b128 v[206:209], v190 offset:22528
	ds_read_b128 v[210:213], v190 offset:23040
	s_waitcnt lgkmcnt(11)
	v_mfma_f32_32x32x16_bf16 v[18:33], v[34:37], v[82:85], v[66:81]
	s_waitcnt lgkmcnt(10)
	v_mfma_f32_32x32x16_bf16 v[34:49], v[154:157], v[82:85], v[66:81]
	s_waitcnt lgkmcnt(9)
	v_mfma_f32_32x32x16_bf16 v[18:33], v[158:161], v[86:89], v[18:33]
	s_waitcnt lgkmcnt(8)
	v_mfma_f32_32x32x16_bf16 v[34:49], v[162:165], v[86:89], v[34:49]
	s_waitcnt lgkmcnt(7)
	v_mfma_f32_32x32x16_bf16 v[18:33], v[166:169], v[90:93], v[18:33]
	s_waitcnt lgkmcnt(6)
	v_mfma_f32_32x32x16_bf16 v[34:49], v[170:173], v[90:93], v[34:49]
	s_waitcnt lgkmcnt(5)
	v_mfma_f32_32x32x16_bf16 v[18:33], v[174:177], v[94:97], v[18:33]
	s_waitcnt lgkmcnt(4)
	v_mfma_f32_32x32x16_bf16 v[34:49], v[178:181], v[94:97], v[34:49]
	s_waitcnt lgkmcnt(3)
	v_mfma_f32_32x32x16_bf16 v[18:33], v[198:201], v[98:101], v[18:33]
	s_waitcnt lgkmcnt(2)
	v_mfma_f32_32x32x16_bf16 v[34:49], v[202:205], v[98:101], v[34:49]
	s_waitcnt lgkmcnt(1)
	v_mfma_f32_32x32x16_bf16 v[18:33], v[206:209], v[102:105], v[18:33]
	s_waitcnt lgkmcnt(0)
	v_mfma_f32_32x32x16_bf16 v[34:49], v[210:213], v[102:105], v[34:49]
	s_nop 15
	s_nop 7

; #define AT_LAS __attribute__((address_space(3)))
; __device__ __forceinline__ s16x4 vtr(AT_LAS const char* p) { return __builtin_bit_cast(s16x4, __builtin_amdgcn_ds_read_tr16_b64_v4i16((AT_LAS v4i16_t*)p)); }
; __device__ __forceinline__ void pv(f32x16 (&o)[2], AT_LAS const char* vp, const u32x4& pw0, const u32x4& pw1, const u32x4& pw2, const u32x4& pw3) {
; #pragma unroll
;     for (int d0 = 0; d0 < 2; ++d0) { s16x4 lo[4], hh[4];
; #pragma unroll
;         for (int ks = 0; ks < 4; ++ks) { lo[ks] = vtr(vp + d0 * 4096 + ks * 1024); hh[ks] = vtr(vp + d0 * 4096 + ks * 1024 + 512); }
;     ...
;         o[d0] = __builtin_amdgcn_mfma_f32_32x32x16_bf16(__builtin_bit_cast(bf16x8, pw0), AT_VF(0), o[d0], 0, 0, 0);
;         o[d0] = __builtin_amdgcn_mfma_f32_32x32x16_bf16(__builtin_bit_cast(bf16x8, pw1), AT_VF(1), o[d0], 0, 0, 0);
;         o[d0] = __builtin_amdgcn_mfma_f32_32x32x16_bf16(__builtin_bit_cast(bf16x8, pw2), AT_VF(2), o[d0], 0, 0, 0);
;         o[d0] = __builtin_amdgcn_mfma_f32_32x32x16_bf16(__builtin_bit_cast(bf16x8, pw3), AT_VF(3), o[d0], 0, 0, 0);
;     ...
;     }
; }
; template <int THRL>
; __device__ __forceinline__ void attn_item(int b, int h, int s, const bf16_t* Q, const bf16_t* KN, const bf16_t* KR, const bf16_t* V, const float* goa  , bf16_t* Y, float* ssqy, AT_LAS char* shm, int wid0) {
;     ...
;             if (late) { if (have) pv(o, vp0 + ((t - 1) & 3) * VSLOTB, pw0, pw1, pw2, pw3);
;                         have = false; if (need) qkt(p0, p1, kp0 + (t & 3) * KSLOTB, qr, negm); }
.Lat0_e_need:
	s_add_i32 s88, s80, 0xffffa000
	s_and_b32 s88, s88, 0x6000
	v_add_u32_e32 v214, s88, v191
	ds_read_b64_tr_b16 v[216:217], v214 offset:49152
	ds_read_b64_tr_b16 v[218:219], v214 offset:49664
	ds_read_b64_tr_b16 v[220:221], v214 offset:50176
	ds_read_b64_tr_b16 v[222:223], v214 offset:50688
	ds_read_b64_tr_b16 v[224:225], v214 offset:51200
	ds_read_b64_tr_b16 v[226:227], v214 offset:51712
	ds_read_b64_tr_b16 v[228:229], v214 offset:52224
	ds_read_b64_tr_b16 v[230:231], v214 offset:52736
	ds_read_b64_tr_b16 v[232:233], v214 offset:53248
	ds_read_b64_tr_b16 v[234:235], v214 offset:53760
	ds_read_b64_tr_b16 v[240:241], v214 offset:54272
	ds_read_b64_tr_b16 v[242:243], v214 offset:54784
	ds_read_b64_tr_b16 v[244:245], v214 offset:55296
	ds_read_b64_tr_b16 v[246:247], v214 offset:55808
	s_branch .LBB13_773
.LBB13_768:
	s_and_b64 vcc, s[96:97], s[92:93]
	s_cbranch_vccz .Lat0_l_slow
	s_and_b32 s88, s80, 0x6000
	v_add_u32_e32 v214, s88, v191
	s_add_i32 s88, s9, -3
	s_and_b32 s88, s88, 3
	s_mulk_i32 s88, 0x3000
	v_add_u32_e32 v215, s88, v190
	ds_read_b64_tr_b16 v[216:217], v214 offset:49152
	ds_read_b64_tr_b16 v[218:219], v214 offset:49664
	ds_read_b64_tr_b16 v[220:221], v214 offset:50176
	ds_read_b64_tr_b16 v[222:223], v214 offset:50688
	ds_read_b64_tr_b16 v[224:225], v214 offset:51200
	ds_read_b64_tr_b16 v[226:227], v214 offset:51712
	ds_read_b64_tr_b16 v[228:229], v214 offset:52224
	ds_read_b64_tr_b16 v[230:231], v214 offset:52736
	ds_read_b64_tr_b16 v[232:233], v214 offset:53248
	ds_read_b64_tr_b16 v[234:235], v214 offset:53760
	ds_read_b64_tr_b16 v[240:241], v214 offset:54272
	ds_read_b64_tr_b16 v[242:243], v214 offset:54784
	ds_read_b64_tr_b16 v[244:245], v214 offset:55296
	ds_read_b64_tr_b16 v[246:247], v214 offset:55808
	ds_read_b64_tr_b16 v[248:249], v214 offset:56320
	s_waitcnt lgkmcnt(13)
	v_mfma_f32_32x32x16_bf16 v[50:65], v[110:113], v[216:219], v[50:65]
	ds_read_b64_tr_b16 v[250:251], v214 offset:56832
	ds_read_b128 v[34:37], v215
	s_waitcnt lgkmcnt(13)
	v_mfma_f32_32x32x16_bf16 v[50:65], v[106:109], v[220:223], v[50:65]
	ds_read_b128 v[154:157], v215 offset:512
	ds_read_b128 v[158:161], v215 offset:2048
	s_waitcnt lgkmcnt(13)
	v_mfma_f32_32x32x16_bf16 v[50:65], v[118:121], v[224:227], v[50:65]
	ds_read_b128 v[162:165], v215 offset:2560
	ds_read_b128 v[166:169], v215 offset:4096
	s_waitcnt lgkmcnt(13)
	v_mfma_f32_32x32x16_bf16 v[50:65], v[114:117], v[228:231], v[50:65]
	ds_read_b128 v[170:173], v215 offset:4608
	ds_read_b128 v[174:177], v215 offset:6144
	s_waitcnt lgkmcnt(13)
	v_mfma_f32_32x32x16_bf16 v[2:17], v[110:113], v[232:235], v[2:17]
	ds_read_b128 v[178:181], v215 offset:6656
	ds_read_b128 v[198:201], v215 offset:8192
	s_waitcnt lgkmcnt(13)
	v_mfma_f32_32x32x16_bf16 v[2:17], v[106:109], v[240:243], v[2:17]
	ds_read_b128 v[202:205], v215 offset:8704
	ds_read_b128 v[206:209], v215 offset:10240
	s_waitcnt lgkmcnt(13)
	v_mfma_f32_32x32x16_bf16 v[2:17], v[118:121], v[244:247], v[2:17]
	ds_read_b128 v[210:213], v215 offset:10752
	s_waitcnt lgkmcnt(12)
	v_mfma_f32_32x32x16_bf16 v[2:17], v[114:117], v[248:251], v[2:17]
	s_waitcnt lgkmcnt(11)
	v_mfma_f32_32x32x16_bf16 v[18:33], v[34:37], v[82:85], v[66:81]
	s_waitcnt lgkmcnt(10)
	v_mfma_f32_32x32x16_bf16 v[34:49], v[154:157], v[82:85], v[66:81]
	s_waitcnt lgkmcnt(9)
	v_mfma_f32_32x32x16_bf16 v[18:33], v[158:161], v[86:89], v[18:33]
	s_waitcnt lgkmcnt(8)
	v_mfma_f32_32x32x16_bf16 v[34:49], v[162:165], v[86:89], v[34:49]
	s_waitcnt lgkmcnt(7)
	v_mfma_f32_32x32x16_bf16 v[18:33], v[166:169], v[90:93], v[18:33]
	s_waitcnt lgkmcnt(6)
	v_mfma_f32_32x32x16_bf16 v[34:49], v[170:173], v[90:93], v[34:49]
	s_waitcnt lgkmcnt(5)
	v_mfma_f32_32x32x16_bf16 v[18:33], v[174:177], v[94:97], v[18:33]
	s_waitcnt lgkmcnt(4)
	v_mfma_f32_32x32x16_bf16 v[34:49], v[178:181], v[94:97], v[34:49]
	s_waitcnt lgkmcnt(3)
	v_mfma_f32_32x32x16_bf16 v[18:33], v[198:201], v[98:101], v[18:33]
	s_waitcnt lgkmcnt(2)
	v_mfma_f32_32x32x16_bf16 v[34:49], v[202:205], v[98:101], v[34:49]
	s_waitcnt lgkmcnt(1)
	v_mfma_f32_32x32x16_bf16 v[18:33], v[206:209], v[102:105], v[18:33]
	s_waitcnt lgkmcnt(0)
	v_mfma_f32_32x32x16_bf16 v[34:49], v[210:213], v[102:105], v[34:49]
	s_mov_b64 s[96:97], 0
	s_nop 7
	s_nop 3
	s_branch .LBB13_773

; #define AT_LAS __attribute__((address_space(3)))
; __device__ __forceinline__ void qkt(f32x16& p0, f32x16& p1, AT_LAS const char* kb, const bf16x8 (&qr)[6], const f32x16& negm) {
;     bf16x8 kf[12];
; #pragma unroll
;     for (int d0 = 0; d0 < 6; ++d0) { kf[2 * d0] = *(AT_LAS const bf16x8*)(kb + d0 * 2048); kf[2 * d0 + 1] = *(AT_LAS const bf16x8*)(kb + d0 * 2048 + 512); }
;     __builtin_amdgcn_sched_barrier(0);
;     p0 = __builtin_amdgcn_mfma_f32_32x32x16_bf16(kf[0], qr[0], negm, 0, 0, 0); p1 = __builtin_amdgcn_mfma_f32_32x32x16_bf16(kf[1], qr[0], negm, 0, 0, 0);
; #pragma unroll
;     for (int d0 = 1; d0 < 6; ++d0) { p0 = __builtin_amdgcn_mfma_f32_32x32x16_bf16(kf[2 * d0], qr[d0], p0, 0, 0, 0); p1 = __builtin_amdgcn_mfma_f32_32x32x16_bf16(kf[2 * d0 + 1], qr[d0], p1, 0, 0, 0); }
;     asm volatile("s_nop 15\n\ts_nop 7" : "+v"(p0), "+v"(p1));
; }
; template <int THRL>
; __device__ __forceinline__ void attn_item(int b, int h, int s, const bf16_t* Q, const bf16_t* KN, const bf16_t* KR, const bf16_t* V, const float* goa  , bf16_t* Y, float* ssqy, AT_LAS char* shm, int wid0) {
;     ...
;             if (late) { if (have) pv(o, vp0 + ((t - 1) & 3) * VSLOTB, pw0, pw1, pw2, pw3);
;                         have = false; if (need) qkt(p0, p1, kp0 + (t & 3) * KSLOTB, qr, negm); }
.LBB13_770:
	s_andn2_b64 vcc, exec, s[92:93]
	s_cbranch_vccnz .LBB13_772
	s_add_i32 s88, s9, -3
	s_and_b32 s88, s88, 3
	s_mulk_i32 s88, 0x3000
	v_add_u32_e32 v0, s88, v190
	ds_read_b128 v[34:37], v0
	ds_read_b128 v[154:157], v0 offset:512
	ds_read_b128 v[158:161], v0 offset:2048
	ds_read_b128 v[162:165], v0 offset:2560
	ds_read_b128 v[166:169], v0 offset:4096
	ds_read_b128 v[170:173], v0 offset:4608
	ds_read_b128 v[174:177], v0 offset:6144
	ds_read_b128 v[178:181], v0 offset:6656
	ds_read_b128 v[198:201], v0 offset:8192
	ds_read_b128 v[202:205], v0 offset:8704
	ds_read_b128 v[206:209], v0 offset:10240
	ds_read_b128 v[210:213], v0 offset:10752
	s_waitcnt lgkmcnt(11)
	v_mfma_f32_32x32x16_bf16 v[18:33], v[34:37], v[82:85], v[66:81]
	s_waitcnt lgkmcnt(10)
	v_mfma_f32_32x32x16_bf16 v[34:49], v[154:157], v[82:85], v[66:81]
	s_waitcnt lgkmcnt(9)
	v_mfma_f32_32x32x16_bf16 v[18:33], v[158:161], v[86:89], v[18:33]
	s_waitcnt lgkmcnt(8)
	v_mfma_f32_32x32x16_bf16 v[34:49], v[162:165], v[86:89], v[34:49]
	s_waitcnt lgkmcnt(7)
	v_mfma_f32_32x32x16_bf16 v[18:33], v[166:169], v[90:93], v[18:33]
	s_waitcnt lgkmcnt(6)
	v_mfma_f32_32x32x16_bf16 v[34:49], v[170:173], v[90:93], v[34:49]
	s_waitcnt lgkmcnt(5)
	v_mfma_f32_32x32x16_bf16 v[18:33], v[174:177], v[94:97], v[18:33]
	s_waitcnt lgkmcnt(4)
	v_mfma_f32_32x32x16_bf16 v[34:49], v[178:181], v[94:97], v[34:49]
	s_waitcnt lgkmcnt(3)
	v_mfma_f32_32x32x16_bf16 v[18:33], v[198:201], v[98:101], v[18:33]
	s_waitcnt lgkmcnt(2)
	v_mfma_f32_32x32x16_bf16 v[34:49], v[202:205], v[98:101], v[34:49]
	s_waitcnt lgkmcnt(1)
	v_mfma_f32_32x32x16_bf16 v[18:33], v[206:209], v[102:105], v[18:33]
	s_waitcnt lgkmcnt(0)
	v_mfma_f32_32x32x16_bf16 v[34:49], v[210:213], v[102:105], v[34:49]
	s_nop 15
	s_nop 7

; #define AT_LAS __attribute__((address_space(3)))
; __device__ __forceinline__ s16x4 vtr(AT_LAS const char* p) { return __builtin_bit_cast(s16x4, __builtin_amdgcn_ds_read_tr16_b64_v4i16((AT_LAS v4i16_t*)p)); }
; #define AT_PK(P, B) cvtpk_s(P[B], P[B + 1])
; __device__ __forceinline__ void pv(f32x16 (&o)[2], AT_LAS const char* vp, const u32x4& pw0, const u32x4& pw1, const u32x4& pw2, const u32x4& pw3) {
; #pragma unroll
;     for (int d0 = 0; d0 < 2; ++d0) { s16x4 lo[4], hh[4];
; #pragma unroll
;         for (int ks = 0; ks < 4; ++ks) { lo[ks] = vtr(vp + d0 * 4096 + ks * 1024); hh[ks] = vtr(vp + d0 * 4096 + ks * 1024 + 512); }
;     ...
;         o[d0] = __builtin_amdgcn_mfma_f32_32x32x16_bf16(__builtin_bit_cast(bf16x8, pw0), AT_VF(0), o[d0], 0, 0, 0);
;         o[d0] = __builtin_amdgcn_mfma_f32_32x32x16_bf16(__builtin_bit_cast(bf16x8, pw1), AT_VF(1), o[d0], 0, 0, 0);
;         o[d0] = __builtin_amdgcn_mfma_f32_32x32x16_bf16(__builtin_bit_cast(bf16x8, pw2), AT_VF(2), o[d0], 0, 0, 0);
;         o[d0] = __builtin_amdgcn_mfma_f32_32x32x16_bf16(__builtin_bit_cast(bf16x8, pw3), AT_VF(3), o[d0], 0, 0, 0);
;     ...
;     }
; }
; template <int THRL>
; __device__ __forceinline__ void attn_item(int b, int h, int s, const bf16_t* Q, const bf16_t* KN, const bf16_t* KR, const bf16_t* V, const float* goa  , bf16_t* Y, float* ssqy, AT_LAS char* shm, int wid0) {
;     ...
;                 float sacc = 0.f;
; #pragma unroll
;                 for (int r = 0; r < 16; ++r) { p0[r] = __builtin_amdgcn_exp2f(p0[r]); p1[r] = __builtin_amdgcn_exp2f(p1[r]); sacc += p0[r] + p1[r]; }
;                 l_reg += sacc;
;     ...
;                 pw0 = (u32x4){AT_PK(p0, 0), AT_PK(p0, 2), AT_PK(p0, 4), AT_PK(p0, 6)}; pw1 = (u32x4){AT_PK(p0, 8), AT_PK(p0, 10), AT_PK(p0, 12), AT_PK(p0, 14)};
;                 pw2 = (u32x4){AT_PK(p1, 0), AT_PK(p1, 2), AT_PK(p1, 4), AT_PK(p1, 6)}; pw3 = (u32x4){AT_PK(p1, 8), AT_PK(p1, 10), AT_PK(p1, 12), AT_PK(p1, 14)};
;     ...
;                 if (late) have = true;
;                 else pv(o, vp0 + (t & 3) * VSLOTB, pw0, pw1, pw2, pw3);
.LBB13_779:
	v_exp_f32_e32 v18, v18
	v_exp_f32_e32 v34, v34
	v_exp_f32_e32 v0, v19
	v_exp_f32_e32 v154, v35
	v_exp_f32_e32 v20, v20
	v_exp_f32_e32 v36, v36
	v_exp_f32_e32 v168, v21
	v_exp_f32_e32 v156, v37
	v_exp_f32_e32 v22, v22
	v_exp_f32_e32 v38, v38
	v_exp_f32_e32 v170, v23
	v_exp_f32_e32 v158, v39
	v_exp_f32_e32 v24, v24
	v_exp_f32_e32 v40, v40
	v_exp_f32_e32 v172, v25
	v_exp_f32_e32 v160, v41
	v_exp_f32_e32 v26, v26
	v_exp_f32_e32 v42, v42
	v_exp_f32_e32 v174, v27
	v_exp_f32_e32 v162, v43
	v_exp_f32_e32 v28, v28
	v_exp_f32_e32 v44, v44
	v_exp_f32_e32 v176, v29
	v_exp_f32_e32 v164, v45
	v_exp_f32_e32 v30, v30
	v_exp_f32_e32 v46, v46
	v_exp_f32_e32 v178, v31
	v_exp_f32_e32 v166, v47
	v_exp_f32_e32 v32, v32
	v_exp_f32_e32 v48, v48
	v_exp_f32_e32 v33, v33
	v_exp_f32_e32 v49, v49
	v_cvt_pk_bf16_f32 v110, v18, v0
	v_cvt_pk_bf16_f32 v111, v20, v168
	v_cvt_pk_bf16_f32 v112, v22, v170
	v_cvt_pk_bf16_f32 v113, v24, v172
	v_cvt_pk_bf16_f32 v106, v26, v174
	v_cvt_pk_bf16_f32 v107, v28, v176
	v_cvt_pk_bf16_f32 v108, v30, v178
	v_cvt_pk_bf16_f32 v109, v32, v33
	v_cvt_pk_bf16_f32 v118, v34, v154
	v_cvt_pk_bf16_f32 v119, v36, v156
	v_cvt_pk_bf16_f32 v120, v38, v158
	v_cvt_pk_bf16_f32 v121, v40, v160
	v_cvt_pk_bf16_f32 v114, v42, v162
	v_cvt_pk_bf16_f32 v115, v44, v164
	v_cvt_pk_bf16_f32 v116, v46, v166
	s_and_b64 vcc, exec, s[76:77]
	v_cvt_pk_bf16_f32 v117, v48, v49
	s_cbranch_vccnz .LBB13_781
	ds_read_b64_tr_b16 v[248:249], v214 offset:56320
	ds_read_b64_tr_b16 v[250:251], v214 offset:56832
	s_waitcnt lgkmcnt(2)
	v_mfma_f32_32x32x16_bf16 v[50:65], v[110:113], v[216:219], v[50:65]
	v_mfma_f32_32x32x16_bf16 v[50:65], v[106:109], v[220:223], v[50:65]
	v_mfma_f32_32x32x16_bf16 v[50:65], v[118:121], v[224:227], v[50:65]
	v_mfma_f32_32x32x16_bf16 v[50:65], v[114:117], v[228:231], v[50:65]
	v_mfma_f32_32x32x16_bf16 v[2:17], v[110:113], v[232:235], v[2:17]
	v_mfma_f32_32x32x16_bf16 v[2:17], v[106:109], v[240:243], v[2:17]
	v_mfma_f32_32x32x16_bf16 v[2:17], v[118:121], v[244:247], v[2:17]
	s_waitcnt lgkmcnt(0)
	v_mfma_f32_32x32x16_bf16 v[2:17], v[114:117], v[248:251], v[2:17]
	s_branch .LBB13_782

; #define AT_LAS __attribute__((address_space(3)))
; __device__ __forceinline__ void qkt(f32x16& p0, f32x16& p1, AT_LAS const char* kb, const bf16x8 (&qr)[6], const f32x16& negm) {
;     bf16x8 kf[12];
; #pragma unroll
;     for (int d0 = 0; d0 < 6; ++d0) { kf[2 * d0] = *(AT_LAS const bf16x8*)(kb + d0 * 2048); kf[2 * d0 + 1] = *(AT_LAS const bf16x8*)(kb + d0 * 2048 + 512); }
;     __builtin_amdgcn_sched_barrier(0);
;     p0 = __builtin_amdgcn_mfma_f32_32x32x16_bf16(kf[0], qr[0], negm, 0, 0, 0); p1 = __builtin_amdgcn_mfma_f32_32x32x16_bf16(kf[1], qr[0], negm, 0, 0, 0);
; #pragma unroll
;     for (int d0 = 1; d0 < 6; ++d0) { p0 = __builtin_amdgcn_mfma_f32_32x32x16_bf16(kf[2 * d0], qr[d0], p0, 0, 0, 0); p1 = __builtin_amdgcn_mfma_f32_32x32x16_bf16(kf[2 * d0 + 1], qr[d0], p1, 0, 0, 0); }
;     asm volatile("s_nop 15\n\ts_nop 7" : "+v"(p0), "+v"(p1));
; }
; template <int THRL>
; __device__ __forceinline__ void attn_item(int b, int h, int s, const bf16_t* Q, const bf16_t* KN, const bf16_t* KR, const bf16_t* V, const float* goa  , bf16_t* Y, float* ssqy, AT_LAS char* shm, int wid0) {
;     ...
;             if (!late) { if (t + 1 < NT && (jb + 1) <= wq) qkt(p0, p1, kp0 + ((t + 1) & 3) * KSLOTB, qr, negm); }
.LBB13_783:
	s_add_i32 s92, s9, -2
	s_cmp_lt_u32 s92, s79
	s_cselect_b64 vcc, -1, 0
	s_cmp_lt_i32 s84, s2
	s_cselect_b64 s[88:89], -1, 0
	s_and_b64 s[88:89], vcc, s[88:89]
	s_andn2_b64 vcc, exec, s[88:89]
	s_cbranch_vccnz .LBB13_764
	s_and_b32 s84, s92, 3
	s_mulk_i32 s84, 0x3000
	v_add_u32_e32 v0, s84, v190
	ds_read_b128 v[34:37], v0
	ds_read_b128 v[154:157], v0 offset:512
	ds_read_b128 v[158:161], v0 offset:2048
	ds_read_b128 v[162:165], v0 offset:2560
	ds_read_b128 v[166:169], v0 offset:4096
	ds_read_b128 v[170:173], v0 offset:4608
	ds_read_b128 v[174:177], v0 offset:6144
	ds_read_b128 v[178:181], v0 offset:6656
	ds_read_b128 v[198:201], v0 offset:8192
	ds_read_b128 v[202:205], v0 offset:8704
	ds_read_b128 v[206:209], v0 offset:10240
	ds_read_b128 v[210:213], v0 offset:10752
	s_waitcnt lgkmcnt(11)
	v_mfma_f32_32x32x16_bf16 v[18:33], v[34:37], v[82:85], v[66:81]
	s_waitcnt lgkmcnt(10)
	v_mfma_f32_32x32x16_bf16 v[34:49], v[154:157], v[82:85], v[66:81]
	s_waitcnt lgkmcnt(9)
	v_mfma_f32_32x32x16_bf16 v[18:33], v[158:161], v[86:89], v[18:33]
	s_waitcnt lgkmcnt(8)
	v_mfma_f32_32x32x16_bf16 v[34:49], v[162:165], v[86:89], v[34:49]
	s_waitcnt lgkmcnt(7)
	v_mfma_f32_32x32x16_bf16 v[18:33], v[166:169], v[90:93], v[18:33]
	s_waitcnt lgkmcnt(6)
	v_mfma_f32_32x32x16_bf16 v[34:49], v[170:173], v[90:93], v[34:49]
	s_waitcnt lgkmcnt(5)
	v_mfma_f32_32x32x16_bf16 v[18:33], v[174:177], v[94:97], v[18:33]
	s_waitcnt lgkmcnt(4)
	v_mfma_f32_32x32x16_bf16 v[34:49], v[178:181], v[94:97], v[34:49]
	s_waitcnt lgkmcnt(3)
	v_mfma_f32_32x32x16_bf16 v[18:33], v[198:201], v[98:101], v[18:33]
	s_waitcnt lgkmcnt(2)
	v_mfma_f32_32x32x16_bf16 v[34:49], v[202:205], v[98:101], v[34:49]
	s_waitcnt lgkmcnt(1)
	v_mfma_f32_32x32x16_bf16 v[18:33], v[206:209], v[102:105], v[18:33]
	s_waitcnt lgkmcnt(0)
	v_mfma_f32_32x32x16_bf16 v[34:49], v[210:213], v[102:105], v[34:49]
	s_nop 15
	s_nop 7
	s_branch .LBB13_764

; #define AT_LAS __attribute__((address_space(3)))
; #define AT_WAIT_BAR(N) asm volatile("s_waitcnt vmcnt(" #N ") lgkmcnt(0)\n\ts_barrier" ::: "memory")
; __device__ __forceinline__ void qkt(f32x16& p0, f32x16& p1, AT_LAS const char* kb, const bf16x8 (&qr)[6], const f32x16& negm) {
;     bf16x8 kf[12];
; #pragma unroll
;     for (int d0 = 0; d0 < 6; ++d0) { kf[2 * d0] = *(AT_LAS const bf16x8*)(kb + d0 * 2048); kf[2 * d0 + 1] = *(AT_LAS const bf16x8*)(kb + d0 * 2048 + 512); }
;     __builtin_amdgcn_sched_barrier(0);
;     p0 = __builtin_amdgcn_mfma_f32_32x32x16_bf16(kf[0], qr[0], negm, 0, 0, 0); p1 = __builtin_amdgcn_mfma_f32_32x32x16_bf16(kf[1], qr[0], negm, 0, 0, 0);
; #pragma unroll
;     for (int d0 = 1; d0 < 6; ++d0) { p0 = __builtin_amdgcn_mfma_f32_32x32x16_bf16(kf[2 * d0], qr[d0], p0, 0, 0, 0); p1 = __builtin_amdgcn_mfma_f32_32x32x16_bf16(kf[2 * d0 + 1], qr[d0], p1, 0, 0, 0); }
;     asm volatile("s_nop 15\n\ts_nop 7" : "+v"(p0), "+v"(p1));
; }
; template <int THRL>
; __device__ __forceinline__ void attn_item(int b, int h, int s, const bf16_t* Q, const bf16_t* KN, const bf16_t* KR, const bf16_t* V, const float* goa  , bf16_t* Y, float* ssqy, AT_LAS char* shm, int wid0) {
;     ...
;         float mhat = 0.f, l_reg = 0.f; f32x16 o[2]; o[0] = f32x16{}; o[1] = f32x16{};
;         f32x16 negm = f32x16{}; asm volatile("" : "+v"(negm));
;         u32x4 pw0 = u32x4{}, pw1 = u32x4{}, pw2 = u32x4{}, pw3 = u32x4{}; bool have = false;
;         f32x16 p0 = f32x16{}, p1 = f32x16{};
;         AT_WAIT_BAR(6);
;         if (!late) qkt(p0, p1, kp0, qr, negm);
.LBB13_1726:
	v_mov_b32_e32 v14, v1
	v_mov_b32_e32 v15, v1
	v_mov_b32_e32 v0, v1
	s_waitcnt lgkmcnt(0)
	v_mov_b32_e32 v2, v1
	v_mov_b32_e32 v3, v1
	v_mov_b32_e32 v4, v1
	v_mov_b32_e32 v5, v1
	v_mov_b32_e32 v6, v1
	v_mov_b32_e32 v7, v1
	v_mov_b32_e32 v8, v1
	v_mov_b32_e32 v9, v1
	v_mov_b32_e32 v10, v1
	v_mov_b32_e32 v11, v1
	v_mov_b32_e32 v12, v1
	v_mov_b32_e32 v13, v1
	v_mov_b64_e32 v[80:81], v[14:15]
	v_mov_b64_e32 v[78:79], v[12:13]
	v_mov_b64_e32 v[76:77], v[10:11]
	v_mov_b64_e32 v[74:75], v[8:9]
	v_mov_b64_e32 v[72:73], v[6:7]
	v_mov_b64_e32 v[70:71], v[4:5]
	v_mov_b64_e32 v[68:69], v[2:3]
	v_mov_b64_e32 v[66:67], v[0:1]
	s_waitcnt vmcnt(6) lgkmcnt(0)
	s_barrier
	v_cndmask_b32_e64 v16, 0, 1, s[0:1]
	v_cmp_ne_u32_e64 s[76:77], 1, v16
	s_andn2_b64 vcc, exec, s[0:1]
	s_cbranch_vccnz .LBB13_1728
	ds_read_b128 v[2:5], v190
	ds_read_b128 v[6:9], v190 offset:512
	ds_read_b128 v[10:13], v190 offset:2048
	ds_read_b128 v[14:17], v190 offset:2560
	ds_read_b128 v[50:53], v190 offset:4096
	ds_read_b128 v[54:57], v190 offset:4608
	ds_read_b128 v[58:61], v190 offset:6144
	ds_read_b128 v[62:65], v190 offset:6656
	ds_read_b128 v[106:109], v190 offset:8192
	ds_read_b128 v[110:113], v190 offset:8704
	ds_read_b128 v[114:117], v190 offset:10240
	ds_read_b128 v[118:121], v190 offset:10752
	s_waitcnt lgkmcnt(11)
	v_mfma_f32_32x32x16_bf16 v[18:33], v[2:5], v[82:85], v[66:81]
	s_waitcnt lgkmcnt(10)
	v_mfma_f32_32x32x16_bf16 v[34:49], v[6:9], v[82:85], v[66:81]
	s_waitcnt lgkmcnt(9)
	v_mfma_f32_32x32x16_bf16 v[18:33], v[10:13], v[86:89], v[18:33]
	s_waitcnt lgkmcnt(8)
	v_mfma_f32_32x32x16_bf16 v[34:49], v[14:17], v[86:89], v[34:49]
	s_waitcnt lgkmcnt(7)
	v_mfma_f32_32x32x16_bf16 v[18:33], v[50:53], v[90:93], v[18:33]
	s_waitcnt lgkmcnt(6)
	v_mfma_f32_32x32x16_bf16 v[34:49], v[54:57], v[90:93], v[34:49]
	s_waitcnt lgkmcnt(5)
	v_mfma_f32_32x32x16_bf16 v[18:33], v[58:61], v[94:97], v[18:33]
	s_waitcnt lgkmcnt(4)
	v_mfma_f32_32x32x16_bf16 v[34:49], v[62:65], v[94:97], v[34:49]
	s_waitcnt lgkmcnt(3)
	v_mfma_f32_32x32x16_bf16 v[18:33], v[106:109], v[98:101], v[18:33]
	s_waitcnt lgkmcnt(2)
	v_mfma_f32_32x32x16_bf16 v[34:49], v[110:113], v[98:101], v[34:49]
	s_waitcnt lgkmcnt(1)
	v_mfma_f32_32x32x16_bf16 v[18:33], v[114:117], v[102:105], v[18:33]
	s_waitcnt lgkmcnt(0)
	v_mfma_f32_32x32x16_bf16 v[34:49], v[118:121], v[102:105], v[34:49]
	s_nop 15
	s_nop 7
	s_branch .LBB13_1729

; #define AT_WAIT_BAR(N) asm volatile("s_waitcnt vmcnt(" #N ") lgkmcnt(0)\n\ts_barrier" ::: "memory")
; template <int THRL>
; __device__ __forceinline__ void attn_item(int b, int h, int s, const bf16_t* Q, const bf16_t* KN, const bf16_t* KR, const bf16_t* V, const float* goa  , bf16_t* Y, float* ssqy, AT_LAS char* shm, int wid0) {
;     ...
;         const int qb = (ui == 0) ? s : (ui == 1) ? 7 - s : (ui == 2) ? 2 + s : 5 - s; const int q0 = qb * 256;
;         const int NT = (q0 + 256) / KVBLK;
;         float mhat = 0.f, l_reg = 0.f; f32x16 o[2]; o[0] = f32x16{}; o[1] = f32x16{};
;         f32x16 negm = f32x16{}; asm volatile("" : "+v"(negm));
;         u32x4 pw0 = u32x4{}, pw1 = u32x4{}, pw2 = u32x4{}, pw3 = u32x4{}; bool have = false;
;         f32x16 p0 = f32x16{}, p1 = f32x16{};
;         AT_WAIT_BAR(6);
;         if (!late) qkt(p0, p1, kp0, qr, negm);
;         for (int t = 0; t < NT; ++t) {
;             AT_WAIT_BAR(3);
;             AT_DMA(t + 3, t + 2, NT);
;             const int jb = t - (NT - 4);
;             const bool need = jb <= wq;
;             if (late) { if (have) pv(o, vp0 + ((t - 1) & 3) * VSLOTB, pw0, pw1, pw2, pw3);
;                         have = false; if (need) qkt(p0, p1, kp0 + (t & 3) * KSLOTB, qr, negm); }
.LBB13_1729:
	s_cmp_eq_u32 s8, 2
	v_readlane_b32 s3, v238, 57
	s_cselect_b32 s3, s3, s86
	s_cmp_eq_u32 s8, 1
	s_cselect_b64 s[82:83], -1, 0
	s_and_b64 s[4:5], s[82:83], exec
	v_readlane_b32 s4, v238, 59
	s_cselect_b32 s3, s4, s3
	s_cmp_eq_u32 s8, 0
	s_cselect_b64 s[94:95], -1, 0
	s_and_b64 s[4:5], s[94:95], exec
	v_readlane_b32 s4, v238, 58
	v_readlane_b32 s80, v238, 16
	v_readlane_b32 s5, v238, 52
	s_cselect_b32 s9, s4, s3
	s_waitcnt vmcnt(3) lgkmcnt(0)
	s_barrier
	s_add_i32 s5, s5, s80
	s_lshl_b32 s4, s9, 8
	s_mov_b32 s79, m0
	s_mov_b32 m0, s5
	s_nop 0
	global_load_lds_dwordx4 v[144:145], off
	s_mov_b32 m0, s79
	v_readlane_b32 s5, v238, 54
	s_add_i32 s3, s4, 0x100
	s_add_i32 s5, s5, s80
	s_lshr_b32 s3, s3, 6
	s_mov_b32 s79, m0
	s_mov_b32 m0, s5
	s_nop 0
	global_load_lds_dwordx4 v[146:147], off
	s_mov_b32 m0, s79
	s_add_i32 s5, s87, 0x10000
	s_mov_b32 s79, m0
	s_mov_b32 m0, s5
	s_nop 0
	global_load_lds_dwordx4 v[148:149], off
	s_mov_b32 m0, s79
	s_sub_i32 s5, 4, s3
	s_cmp_le_i32 s5, s33
	s_cselect_b64 s[92:93], -1, 0
	s_and_b64 s[80:81], s[90:91], s[92:93]
	s_andn2_b64 vcc, exec, s[80:81]
	s_cbranch_vccnz .LBB13_1731
	ds_read_b128 v[2:5], v190
	ds_read_b128 v[6:9], v190 offset:512
	ds_read_b128 v[10:13], v190 offset:2048
	ds_read_b128 v[14:17], v190 offset:2560
	ds_read_b128 v[50:53], v190 offset:4096
	ds_read_b128 v[54:57], v190 offset:4608
	ds_read_b128 v[58:61], v190 offset:6144
	ds_read_b128 v[62:65], v190 offset:6656
	ds_read_b128 v[106:109], v190 offset:8192
	ds_read_b128 v[110:113], v190 offset:8704
	ds_read_b128 v[114:117], v190 offset:10240
	ds_read_b128 v[118:121], v190 offset:10752
	s_waitcnt lgkmcnt(11)
	v_mfma_f32_32x32x16_bf16 v[18:33], v[2:5], v[82:85], v[66:81]
	s_waitcnt lgkmcnt(10)
	v_mfma_f32_32x32x16_bf16 v[34:49], v[6:9], v[82:85], v[66:81]
	s_waitcnt lgkmcnt(9)
	v_mfma_f32_32x32x16_bf16 v[18:33], v[10:13], v[86:89], v[18:33]
	s_waitcnt lgkmcnt(8)
	v_mfma_f32_32x32x16_bf16 v[34:49], v[14:17], v[86:89], v[34:49]
	s_waitcnt lgkmcnt(7)
	v_mfma_f32_32x32x16_bf16 v[18:33], v[50:53], v[90:93], v[18:33]
	s_waitcnt lgkmcnt(6)
	v_mfma_f32_32x32x16_bf16 v[34:49], v[54:57], v[90:93], v[34:49]
	s_waitcnt lgkmcnt(5)
	v_mfma_f32_32x32x16_bf16 v[18:33], v[58:61], v[94:97], v[18:33]
	s_waitcnt lgkmcnt(4)
	v_mfma_f32_32x32x16_bf16 v[34:49], v[62:65], v[94:97], v[34:49]
	s_waitcnt lgkmcnt(3)
	v_mfma_f32_32x32x16_bf16 v[18:33], v[106:109], v[98:101], v[18:33]
	s_waitcnt lgkmcnt(2)
	v_mfma_f32_32x32x16_bf16 v[34:49], v[110:113], v[98:101], v[34:49]
	s_waitcnt lgkmcnt(1)
	v_mfma_f32_32x32x16_bf16 v[18:33], v[114:117], v[102:105], v[18:33]
	s_waitcnt lgkmcnt(0)
	v_mfma_f32_32x32x16_bf16 v[34:49], v[118:121], v[102:105], v[34:49]
	s_nop 15
	s_nop 7

; #define AT_LAS __attribute__((address_space(3)))
; __device__ __forceinline__ void qkt(f32x16& p0, f32x16& p1, AT_LAS const char* kb, const bf16x8 (&qr)[6], const f32x16& negm) {
;     bf16x8 kf[12];
; #pragma unroll
;     for (int d0 = 0; d0 < 6; ++d0) { kf[2 * d0] = *(AT_LAS const bf16x8*)(kb + d0 * 2048); kf[2 * d0 + 1] = *(AT_LAS const bf16x8*)(kb + d0 * 2048 + 512); }
;     __builtin_amdgcn_sched_barrier(0);
;     p0 = __builtin_amdgcn_mfma_f32_32x32x16_bf16(kf[0], qr[0], negm, 0, 0, 0); p1 = __builtin_amdgcn_mfma_f32_32x32x16_bf16(kf[1], qr[0], negm, 0, 0, 0);
; #pragma unroll
;     for (int d0 = 1; d0 < 6; ++d0) { p0 = __builtin_amdgcn_mfma_f32_32x32x16_bf16(kf[2 * d0], qr[d0], p0, 0, 0, 0); p1 = __builtin_amdgcn_mfma_f32_32x32x16_bf16(kf[2 * d0 + 1], qr[d0], p1, 0, 0, 0); }
;     asm volatile("s_nop 15\n\ts_nop 7" : "+v"(p0), "+v"(p1));
; }
; template <int THRL>
; __device__ __forceinline__ void attn_item(int b, int h, int s, const bf16_t* Q, const bf16_t* KN, const bf16_t* KR, const bf16_t* V, const float* goa  , bf16_t* Y, float* ssqy, AT_LAS char* shm, int wid0) {
;     ...
;             if (!late) { if (t + 1 < NT && (jb + 1) <= wq) qkt(p0, p1, kp0 + ((t + 1) & 3) * KSLOTB, qr, negm); }
.LBB13_1739:
	s_cmp_ge_i32 s5, s33
	s_cselect_b64 s[80:81], -1, 0
	s_or_b64 s[80:81], s[90:91], s[80:81]
	s_andn2_b64 vcc, exec, s[80:81]
	s_cbranch_vccz .LBB13_1741
	ds_read_b128 v[34:37], v190 offset:12288
	ds_read_b128 v[154:157], v190 offset:12800
	ds_read_b128 v[158:161], v190 offset:14336
	ds_read_b128 v[162:165], v190 offset:14848
	ds_read_b128 v[166:169], v190 offset:16384
	ds_read_b128 v[170:173], v190 offset:16896
	ds_read_b128 v[174:177], v190 offset:18432
	ds_read_b128 v[178:181], v190 offset:18944
	ds_read_b128 v[198:201], v190 offset:20480
	ds_read_b128 v[202:205], v190 offset:20992
	ds_read_b128 v[206:209], v190 offset:22528
	ds_read_b128 v[210:213], v190 offset:23040
	s_waitcnt lgkmcnt(11)
	v_mfma_f32_32x32x16_bf16 v[18:33], v[34:37], v[82:85], v[66:81]
	s_waitcnt lgkmcnt(10)
	v_mfma_f32_32x32x16_bf16 v[34:49], v[154:157], v[82:85], v[66:81]
	s_waitcnt lgkmcnt(9)
	v_mfma_f32_32x32x16_bf16 v[18:33], v[158:161], v[86:89], v[18:33]
	s_waitcnt lgkmcnt(8)
	v_mfma_f32_32x32x16_bf16 v[34:49], v[162:165], v[86:89], v[34:49]
	s_waitcnt lgkmcnt(7)
	v_mfma_f32_32x32x16_bf16 v[18:33], v[166:169], v[90:93], v[18:33]
	s_waitcnt lgkmcnt(6)
	v_mfma_f32_32x32x16_bf16 v[34:49], v[170:173], v[90:93], v[34:49]
	s_waitcnt lgkmcnt(5)
	v_mfma_f32_32x32x16_bf16 v[18:33], v[174:177], v[94:97], v[18:33]
	s_waitcnt lgkmcnt(4)
	v_mfma_f32_32x32x16_bf16 v[34:49], v[178:181], v[94:97], v[34:49]
	s_waitcnt lgkmcnt(3)
	v_mfma_f32_32x32x16_bf16 v[18:33], v[198:201], v[98:101], v[18:33]
	s_waitcnt lgkmcnt(2)
	v_mfma_f32_32x32x16_bf16 v[34:49], v[202:205], v[98:101], v[34:49]
	s_waitcnt lgkmcnt(1)
	v_mfma_f32_32x32x16_bf16 v[18:33], v[206:209], v[102:105], v[18:33]
	s_waitcnt lgkmcnt(0)
	v_mfma_f32_32x32x16_bf16 v[34:49], v[210:213], v[102:105], v[34:49]
	s_nop 15
	s_nop 7

; #define AT_LAS __attribute__((address_space(3)))
; __device__ __forceinline__ s16x4 vtr(AT_LAS const char* p) { return __builtin_bit_cast(s16x4, __builtin_amdgcn_ds_read_tr16_b64_v4i16((AT_LAS v4i16_t*)p)); }
; __device__ __forceinline__ void pv(f32x16 (&o)[2], AT_LAS const char* vp, const u32x4& pw0, const u32x4& pw1, const u32x4& pw2, const u32x4& pw3) {
; #pragma unroll
;     for (int d0 = 0; d0 < 2; ++d0) { s16x4 lo[4], hh[4];
; #pragma unroll
;         for (int ks = 0; ks < 4; ++ks) { lo[ks] = vtr(vp + d0 * 4096 + ks * 1024); hh[ks] = vtr(vp + d0 * 4096 + ks * 1024 + 512); }
;     ...
;         o[d0] = __builtin_amdgcn_mfma_f32_32x32x16_bf16(__builtin_bit_cast(bf16x8, pw0), AT_VF(0), o[d0], 0, 0, 0);
;         o[d0] = __builtin_amdgcn_mfma_f32_32x32x16_bf16(__builtin_bit_cast(bf16x8, pw1), AT_VF(1), o[d0], 0, 0, 0);
;         o[d0] = __builtin_amdgcn_mfma_f32_32x32x16_bf16(__builtin_bit_cast(bf16x8, pw2), AT_VF(2), o[d0], 0, 0, 0);
;         o[d0] = __builtin_amdgcn_mfma_f32_32x32x16_bf16(__builtin_bit_cast(bf16x8, pw3), AT_VF(3), o[d0], 0, 0, 0);
;     ...
;     }
; }
; template <int THRL>
; __device__ __forceinline__ void attn_item(int b, int h, int s, const bf16_t* Q, const bf16_t* KN, const bf16_t* KR, const bf16_t* V, const float* goa  , bf16_t* Y, float* ssqy, AT_LAS char* shm, int wid0) {
;     ...
;             if (late) { if (have) pv(o, vp0 + ((t - 1) & 3) * VSLOTB, pw0, pw1, pw2, pw3);
;                         have = false; if (need) qkt(p0, p1, kp0 + (t & 3) * KSLOTB, qr, negm); }
.Lat1_e_need:
	s_add_i32 s88, s9, 0xffffa000
	s_and_b32 s88, s88, 0x6000
	v_add_u32_e32 v214, s88, v191
	ds_read_b64_tr_b16 v[216:217], v214 offset:49152
	ds_read_b64_tr_b16 v[218:219], v214 offset:49664
	ds_read_b64_tr_b16 v[220:221], v214 offset:50176
	ds_read_b64_tr_b16 v[222:223], v214 offset:50688
	ds_read_b64_tr_b16 v[224:225], v214 offset:51200
	ds_read_b64_tr_b16 v[226:227], v214 offset:51712
	ds_read_b64_tr_b16 v[228:229], v214 offset:52224
	ds_read_b64_tr_b16 v[230:231], v214 offset:52736
	ds_read_b64_tr_b16 v[232:233], v214 offset:53248
	ds_read_b64_tr_b16 v[234:235], v214 offset:53760
	ds_read_b64_tr_b16 v[240:241], v214 offset:54272
	ds_read_b64_tr_b16 v[242:243], v214 offset:54784
	ds_read_b64_tr_b16 v[244:245], v214 offset:55296
	ds_read_b64_tr_b16 v[246:247], v214 offset:55808
	s_branch .LBB13_1751
.LBB13_1746:
	s_and_b64 vcc, s[96:97], s[92:93]
	s_cbranch_vccz .Lat1_l_slow
	s_and_b32 s88, s9, 0x6000
	v_add_u32_e32 v214, s88, v191
	s_add_i32 s88, s80, -3
	s_and_b32 s88, s88, 3
	s_mulk_i32 s88, 0x3000
	v_add_u32_e32 v215, s88, v190
	ds_read_b64_tr_b16 v[216:217], v214 offset:49152
	ds_read_b64_tr_b16 v[218:219], v214 offset:49664
	ds_read_b64_tr_b16 v[220:221], v214 offset:50176
	ds_read_b64_tr_b16 v[222:223], v214 offset:50688
	ds_read_b64_tr_b16 v[224:225], v214 offset:51200
	ds_read_b64_tr_b16 v[226:227], v214 offset:51712
	ds_read_b64_tr_b16 v[228:229], v214 offset:52224
	ds_read_b64_tr_b16 v[230:231], v214 offset:52736
	ds_read_b64_tr_b16 v[232:233], v214 offset:53248
	ds_read_b64_tr_b16 v[234:235], v214 offset:53760
	ds_read_b64_tr_b16 v[240:241], v214 offset:54272
	ds_read_b64_tr_b16 v[242:243], v214 offset:54784
	ds_read_b64_tr_b16 v[244:245], v214 offset:55296
	ds_read_b64_tr_b16 v[246:247], v214 offset:55808
	ds_read_b64_tr_b16 v[248:249], v214 offset:56320
	s_waitcnt lgkmcnt(13)
	v_mfma_f32_32x32x16_bf16 v[50:65], v[110:113], v[216:219], v[50:65]
	ds_read_b64_tr_b16 v[250:251], v214 offset:56832
	ds_read_b128 v[34:37], v215
	s_waitcnt lgkmcnt(13)
	v_mfma_f32_32x32x16_bf16 v[50:65], v[106:109], v[220:223], v[50:65]
	ds_read_b128 v[154:157], v215 offset:512
	ds_read_b128 v[158:161], v215 offset:2048
	s_waitcnt lgkmcnt(13)
	v_mfma_f32_32x32x16_bf16 v[50:65], v[118:121], v[224:227], v[50:65]
	ds_read_b128 v[162:165], v215 offset:2560
	ds_read_b128 v[166:169], v215 offset:4096
	s_waitcnt lgkmcnt(13)
	v_mfma_f32_32x32x16_bf16 v[50:65], v[114:117], v[228:231], v[50:65]
	ds_read_b128 v[170:173], v215 offset:4608
	ds_read_b128 v[174:177], v215 offset:6144
	s_waitcnt lgkmcnt(13)
	v_mfma_f32_32x32x16_bf16 v[2:17], v[110:113], v[232:235], v[2:17]
	ds_read_b128 v[178:181], v215 offset:6656
	ds_read_b128 v[198:201], v215 offset:8192
	s_waitcnt lgkmcnt(13)
	v_mfma_f32_32x32x16_bf16 v[2:17], v[106:109], v[240:243], v[2:17]
	ds_read_b128 v[202:205], v215 offset:8704
	ds_read_b128 v[206:209], v215 offset:10240
	s_waitcnt lgkmcnt(13)
	v_mfma_f32_32x32x16_bf16 v[2:17], v[118:121], v[244:247], v[2:17]
	ds_read_b128 v[210:213], v215 offset:10752
	s_waitcnt lgkmcnt(12)
	v_mfma_f32_32x32x16_bf16 v[2:17], v[114:117], v[248:251], v[2:17]
	s_waitcnt lgkmcnt(11)
	v_mfma_f32_32x32x16_bf16 v[18:33], v[34:37], v[82:85], v[66:81]
	s_waitcnt lgkmcnt(10)
	v_mfma_f32_32x32x16_bf16 v[34:49], v[154:157], v[82:85], v[66:81]
	s_waitcnt lgkmcnt(9)
	v_mfma_f32_32x32x16_bf16 v[18:33], v[158:161], v[86:89], v[18:33]
	s_waitcnt lgkmcnt(8)
	v_mfma_f32_32x32x16_bf16 v[34:49], v[162:165], v[86:89], v[34:49]
	s_waitcnt lgkmcnt(7)
	v_mfma_f32_32x32x16_bf16 v[18:33], v[166:169], v[90:93], v[18:33]
	s_waitcnt lgkmcnt(6)
	v_mfma_f32_32x32x16_bf16 v[34:49], v[170:173], v[90:93], v[34:49]
	s_waitcnt lgkmcnt(5)
	v_mfma_f32_32x32x16_bf16 v[18:33], v[174:177], v[94:97], v[18:33]
	s_waitcnt lgkmcnt(4)
	v_mfma_f32_32x32x16_bf16 v[34:49], v[178:181], v[94:97], v[34:49]
	s_waitcnt lgkmcnt(3)
	v_mfma_f32_32x32x16_bf16 v[18:33], v[198:201], v[98:101], v[18:33]
	s_waitcnt lgkmcnt(2)
	v_mfma_f32_32x32x16_bf16 v[34:49], v[202:205], v[98:101], v[34:49]
	s_waitcnt lgkmcnt(1)
	v_mfma_f32_32x32x16_bf16 v[18:33], v[206:209], v[102:105], v[18:33]
	s_waitcnt lgkmcnt(0)
	v_mfma_f32_32x32x16_bf16 v[34:49], v[210:213], v[102:105], v[34:49]
	s_mov_b64 s[96:97], 0
	s_nop 7
	s_nop 3
	s_branch .LBB13_1751

; #define AT_LAS __attribute__((address_space(3)))
; __device__ __forceinline__ void qkt(f32x16& p0, f32x16& p1, AT_LAS const char* kb, const bf16x8 (&qr)[6], const f32x16& negm) {
;     bf16x8 kf[12];
; #pragma unroll
;     for (int d0 = 0; d0 < 6; ++d0) { kf[2 * d0] = *(AT_LAS const bf16x8*)(kb + d0 * 2048); kf[2 * d0 + 1] = *(AT_LAS const bf16x8*)(kb + d0 * 2048 + 512); }
;     __builtin_amdgcn_sched_barrier(0);
;     p0 = __builtin_amdgcn_mfma_f32_32x32x16_bf16(kf[0], qr[0], negm, 0, 0, 0); p1 = __builtin_amdgcn_mfma_f32_32x32x16_bf16(kf[1], qr[0], negm, 0, 0, 0);
; #pragma unroll
;     for (int d0 = 1; d0 < 6; ++d0) { p0 = __builtin_amdgcn_mfma_f32_32x32x16_bf16(kf[2 * d0], qr[d0], p0, 0, 0, 0); p1 = __builtin_amdgcn_mfma_f32_32x32x16_bf16(kf[2 * d0 + 1], qr[d0], p1, 0, 0, 0); }
;     asm volatile("s_nop 15\n\ts_nop 7" : "+v"(p0), "+v"(p1));
; }
; template <int THRL>
; __device__ __forceinline__ void attn_item(int b, int h, int s, const bf16_t* Q, const bf16_t* KN, const bf16_t* KR, const bf16_t* V, const float* goa  , bf16_t* Y, float* ssqy, AT_LAS char* shm, int wid0) {
;     ...
;             if (late) { if (have) pv(o, vp0 + ((t - 1) & 3) * VSLOTB, pw0, pw1, pw2, pw3);
;                         have = false; if (need) qkt(p0, p1, kp0 + (t & 3) * KSLOTB, qr, negm); }
.LBB13_1748:
	s_andn2_b64 vcc, exec, s[92:93]
	s_cbranch_vccnz .LBB13_1750
	s_add_i32 s88, s80, -3
	s_and_b32 s88, s88, 3
	s_mulk_i32 s88, 0x3000
	v_add_u32_e32 v0, s88, v190
	ds_read_b128 v[34:37], v0
	ds_read_b128 v[154:157], v0 offset:512
	ds_read_b128 v[158:161], v0 offset:2048
	ds_read_b128 v[162:165], v0 offset:2560
	ds_read_b128 v[166:169], v0 offset:4096
	ds_read_b128 v[170:173], v0 offset:4608
	ds_read_b128 v[174:177], v0 offset:6144
	ds_read_b128 v[178:181], v0 offset:6656
	ds_read_b128 v[198:201], v0 offset:8192
	ds_read_b128 v[202:205], v0 offset:8704
	ds_read_b128 v[206:209], v0 offset:10240
	ds_read_b128 v[210:213], v0 offset:10752
	s_waitcnt lgkmcnt(11)
	v_mfma_f32_32x32x16_bf16 v[18:33], v[34:37], v[82:85], v[66:81]
	s_waitcnt lgkmcnt(10)
	v_mfma_f32_32x32x16_bf16 v[34:49], v[154:157], v[82:85], v[66:81]
	s_waitcnt lgkmcnt(9)
	v_mfma_f32_32x32x16_bf16 v[18:33], v[158:161], v[86:89], v[18:33]
	s_waitcnt lgkmcnt(8)
	v_mfma_f32_32x32x16_bf16 v[34:49], v[162:165], v[86:89], v[34:49]
	s_waitcnt lgkmcnt(7)
	v_mfma_f32_32x32x16_bf16 v[18:33], v[166:169], v[90:93], v[18:33]
	s_waitcnt lgkmcnt(6)
	v_mfma_f32_32x32x16_bf16 v[34:49], v[170:173], v[90:93], v[34:49]
	s_waitcnt lgkmcnt(5)
	v_mfma_f32_32x32x16_bf16 v[18:33], v[174:177], v[94:97], v[18:33]
	s_waitcnt lgkmcnt(4)
	v_mfma_f32_32x32x16_bf16 v[34:49], v[178:181], v[94:97], v[34:49]
	s_waitcnt lgkmcnt(3)
	v_mfma_f32_32x32x16_bf16 v[18:33], v[198:201], v[98:101], v[18:33]
	s_waitcnt lgkmcnt(2)
	v_mfma_f32_32x32x16_bf16 v[34:49], v[202:205], v[98:101], v[34:49]
	s_waitcnt lgkmcnt(1)
	v_mfma_f32_32x32x16_bf16 v[18:33], v[206:209], v[102:105], v[18:33]
	s_waitcnt lgkmcnt(0)
	v_mfma_f32_32x32x16_bf16 v[34:49], v[210:213], v[102:105], v[34:49]
	s_nop 15
	s_nop 7

; #define AT_LAS __attribute__((address_space(3)))
; __device__ __forceinline__ void qkt(f32x16& p0, f32x16& p1, AT_LAS const char* kb, const bf16x8 (&qr)[6], const f32x16& negm) {
;     bf16x8 kf[12];
; #pragma unroll
;     for (int d0 = 0; d0 < 6; ++d0) { kf[2 * d0] = *(AT_LAS const bf16x8*)(kb + d0 * 2048); kf[2 * d0 + 1] = *(AT_LAS const bf16x8*)(kb + d0 * 2048 + 512); }
;     __builtin_amdgcn_sched_barrier(0);
;     p0 = __builtin_amdgcn_mfma_f32_32x32x16_bf16(kf[0], qr[0], negm, 0, 0, 0); p1 = __builtin_amdgcn_mfma_f32_32x32x16_bf16(kf[1], qr[0], negm, 0, 0, 0);
; #pragma unroll
;     for (int d0 = 1; d0 < 6; ++d0) { p0 = __builtin_amdgcn_mfma_f32_32x32x16_bf16(kf[2 * d0], qr[d0], p0, 0, 0, 0); p1 = __builtin_amdgcn_mfma_f32_32x32x16_bf16(kf[2 * d0 + 1], qr[d0], p1, 0, 0, 0); }
;     asm volatile("s_nop 15\n\ts_nop 7" : "+v"(p0), "+v"(p1));
; }
; template <int THRL>
; __device__ __forceinline__ void attn_item(int b, int h, int s, const bf16_t* Q, const bf16_t* KN, const bf16_t* KR, const bf16_t* V, const float* goa  , bf16_t* Y, float* ssqy, AT_LAS char* shm, int wid0) {
;     ...
;             if (!late) { if (t + 1 < NT && (jb + 1) <= wq) qkt(p0, p1, kp0 + ((t + 1) & 3) * KSLOTB, qr, negm); }
.LBB13_1761:
	s_add_i32 s92, s80, -2
	s_cmp_lt_u32 s92, s3
	s_cselect_b64 vcc, -1, 0
	s_cmp_lt_i32 s84, s33
	s_cselect_b64 s[88:89], -1, 0
	s_and_b64 s[88:89], vcc, s[88:89]
	s_andn2_b64 vcc, exec, s[88:89]
	s_cbranch_vccnz .LBB13_1742
	s_and_b32 s84, s92, 3
	s_mulk_i32 s84, 0x3000
	v_add_u32_e32 v0, s84, v190
	ds_read_b128 v[34:37], v0
	ds_read_b128 v[154:157], v0 offset:512
	ds_read_b128 v[158:161], v0 offset:2048
	ds_read_b128 v[162:165], v0 offset:2560
	ds_read_b128 v[166:169], v0 offset:4096
	ds_read_b128 v[170:173], v0 offset:4608
	ds_read_b128 v[174:177], v0 offset:6144
	ds_read_b128 v[178:181], v0 offset:6656
	ds_read_b128 v[198:201], v0 offset:8192
	ds_read_b128 v[202:205], v0 offset:8704
	ds_read_b128 v[206:209], v0 offset:10240
	ds_read_b128 v[210:213], v0 offset:10752
	s_waitcnt lgkmcnt(11)
	v_mfma_f32_32x32x16_bf16 v[18:33], v[34:37], v[82:85], v[66:81]
	s_waitcnt lgkmcnt(10)
	v_mfma_f32_32x32x16_bf16 v[34:49], v[154:157], v[82:85], v[66:81]
	s_waitcnt lgkmcnt(9)
	v_mfma_f32_32x32x16_bf16 v[18:33], v[158:161], v[86:89], v[18:33]
	s_waitcnt lgkmcnt(8)
	v_mfma_f32_32x32x16_bf16 v[34:49], v[162:165], v[86:89], v[34:49]
	s_waitcnt lgkmcnt(7)
	v_mfma_f32_32x32x16_bf16 v[18:33], v[166:169], v[90:93], v[18:33]
	s_waitcnt lgkmcnt(6)
	v_mfma_f32_32x32x16_bf16 v[34:49], v[170:173], v[90:93], v[34:49]
	s_waitcnt lgkmcnt(5)
	v_mfma_f32_32x32x16_bf16 v[18:33], v[174:177], v[94:97], v[18:33]
	s_waitcnt lgkmcnt(4)
	v_mfma_f32_32x32x16_bf16 v[34:49], v[178:181], v[94:97], v[34:49]
	s_waitcnt lgkmcnt(3)
	v_mfma_f32_32x32x16_bf16 v[18:33], v[198:201], v[98:101], v[18:33]
	s_waitcnt lgkmcnt(2)
	v_mfma_f32_32x32x16_bf16 v[34:49], v[202:205], v[98:101], v[34:49]
	s_waitcnt lgkmcnt(1)
	v_mfma_f32_32x32x16_bf16 v[18:33], v[206:209], v[102:105], v[18:33]
	s_waitcnt lgkmcnt(0)
	v_mfma_f32_32x32x16_bf16 v[34:49], v[210:213], v[102:105], v[34:49]
	s_nop 15
	s_nop 7
	s_branch .LBB13_1742

; __global__ void __launch_bounds__(NWAVES * 64, 2) mk_fwd(Args args) {
	.amdhsa_kernel _Z6mk_fwd4Args
		.amdhsa_group_segment_fixed_size 0
		.amdhsa_private_segment_fixed_size 0
		.amdhsa_kernarg_size 448
		.amdhsa_user_sgpr_count 2
		.amdhsa_user_sgpr_dispatch_ptr 0
		.amdhsa_user_sgpr_queue_ptr 0
		.amdhsa_user_sgpr_kernarg_segment_ptr 1
		.amdhsa_user_sgpr_dispatch_id 0
		.amdhsa_user_sgpr_kernarg_preload_length 0
		.amdhsa_user_sgpr_kernarg_preload_offset 0
		.amdhsa_user_sgpr_private_segment_size 0
		.amdhsa_uses_dynamic_stack 0
		.amdhsa_enable_private_segment 0
		.amdhsa_system_sgpr_workgroup_id_x 1
		.amdhsa_system_sgpr_workgroup_id_y 0
		.amdhsa_system_sgpr_workgroup_id_z 0
		.amdhsa_system_sgpr_workgroup_info 0
		.amdhsa_system_vgpr_workitem_id 0
		.amdhsa_next_free_vgpr 256
		.amdhsa_next_free_sgpr 98
		.amdhsa_accum_offset 256
		.amdhsa_reserve_vcc 1
		.amdhsa_float_round_mode_32 0
		.amdhsa_float_round_mode_16_64 0
		.amdhsa_float_denorm_mode_32 3
		.amdhsa_float_denorm_mode_16_64 3
		.amdhsa_dx10_clamp 1
		.amdhsa_ieee_mode 1
		.amdhsa_fp16_overflow 0
		.amdhsa_tg_split 0
		.amdhsa_exception_fp_ieee_invalid_op 0
		.amdhsa_exception_fp_denorm_src 0
		.amdhsa_exception_fp_ieee_div_zero 0
		.amdhsa_exception_fp_ieee_overflow 0
		.amdhsa_exception_fp_ieee_underflow 0
		.amdhsa_exception_fp_ieee_inexact 0
		.amdhsa_exception_int_div_zero 0
	.end_amdhsa_kernel

; __device__ __forceinline__ bf16_t f2bf(float f) { unsigned u = __float_as_uint(f); return (bf16_t)((u + 0x7fffu + ((u >> 16) & 1u)) >> 16); }
; __global__ void k_rope_table(const int* pos, float* rope) {
;     const int idx = blockIdx.x * blockDim.x + threadIdx.x; if (idx >= T * 16) return;
;     const int t = idx >> 4, i = idx & 15;
;     const float freq = powf(10000.0f, -(float)(2 * i) / 32.0f);
;     const float ang = (float)pos[t] * freq;
;     rope[t * 32 + i] = cosf(ang); rope[t * 32 + 16 + i] = sinf(ang);
; }
; __global__ void k_prep_w(const float* W, int K, int N, bf16_t* out, int Nphys, int mode) {
;     const size_t idx = (size_t)blockIdx.x * blockDim.x + threadIdx.x; if (idx >= (size_t)Nphys * K) return;
;     const int p = (int)(idx / K), k = (int)(idx % K);
;     const int s = mode == 1 ? win_src(p) : p;
;     out[idx] = (s >= 0 && s < N) ? f2bf(W[(size_t)k * N + s]) : (bf16_t)0;
; }
amdhsa.kernels:
  - .agpr_count:     0
    .args:
      - .address_space:  global
        .offset:         0
        .size:           8
        .value_kind:     global_buffer
      - .address_space:  global
        .offset:         8
        .size:           8
        .value_kind:     global_buffer
      - .offset:         16
        .size:           4
        .value_kind:     hidden_block_count_x
      - .offset:         20
        .size:           4
        .value_kind:     hidden_block_count_y
      - .offset:         24
        .size:           4
        .value_kind:     hidden_block_count_z
      - .offset:         28
        .size:           2
        .value_kind:     hidden_group_size_x
      - .offset:         30
        .size:           2
        .value_kind:     hidden_group_size_y
      - .offset:         32
        .size:           2
        .value_kind:     hidden_group_size_z
      - .offset:         34
        .size:           2
        .value_kind:     hidden_remainder_x
      - .offset:         36
        .size:           2
        .value_kind:     hidden_remainder_y
      - .offset:         38
        .size:           2
        .value_kind:     hidden_remainder_z
      - .offset:         56
        .size:           8
        .value_kind:     hidden_global_offset_x
      - .offset:         64
        .size:           8
        .value_kind:     hidden_global_offset_y
      - .offset:         72
        .size:           8
        .value_kind:     hidden_global_offset_z
      - .offset:         80
        .size:           2
        .value_kind:     hidden_grid_dims
    .group_segment_fixed_size: 0
    .kernarg_segment_align: 8
    .kernarg_segment_size: 272
    .language:       OpenCL C
    .language_version:
      - 2
      - 0
    .max_flat_workgroup_size: 1024
    .name:           _Z12k_rope_tablePKiPf
    .private_segment_fixed_size: 0
    .sgpr_count:     18
    .sgpr_spill_count: 0
    .symbol:         _Z12k_rope_tablePKiPf.kd
    .uniform_work_group_size: 1
    .uses_dynamic_stack: false
    .vgpr_count:     22
    .vgpr_spill_count: 0
    .wavefront_size: 64
  - .agpr_count:     0
    .args:
      - .address_space:  global
        .offset:         0
        .size:           8
        .value_kind:     global_buffer
      - .offset:         8
        .size:           4
        .value_kind:     by_value
      - .offset:         12
        .size:           4
        .value_kind:     by_value
      - .address_space:  global
        .offset:         16
        .size:           8
        .value_kind:     global_buffer
      - .offset:         24
        .size:           4
        .value_kind:     by_value
      - .offset:         28
        .size:           4
        .value_kind:     by_value
      - .offset:         32
        .size:           4
        .value_kind:     hidden_block_count_x
      - .offset:         36
        .size:           4
        .value_kind:     hidden_block_count_y
      - .offset:         40
        .size:           4
        .value_kind:     hidden_block_count_z
      - .offset:         44
        .size:           2
        .value_kind:     hidden_group_size_x
      - .offset:         46
        .size:           2
        .value_kind:     hidden_group_size_y
      - .offset:         48
        .size:           2
        .value_kind:     hidden_group_size_z
      - .offset:         50
        .size:           2
        .value_kind:     hidden_remainder_x
      - .offset:         52
        .size:           2
        .value_kind:     hidden_remainder_y
      - .offset:         54
        .size:           2
        .value_kind:     hidden_remainder_z
      - .offset:         72
        .size:           8
        .value_kind:     hidden_global_offset_x
      - .offset:         80
        .size:           8
        .value_kind:     hidden_global_offset_y
      - .offset:         88
        .size:           8
        .value_kind:     hidden_global_offset_z
      - .offset:         96
        .size:           2
        .value_kind:     hidden_grid_dims
    .group_segment_fixed_size: 0
    .kernarg_segment_align: 8
    .kernarg_segment_size: 288
    .language:       OpenCL C
    .language_version:
      - 2
      - 0
    .max_flat_workgroup_size: 1024
    .name:           _Z8k_prep_wPKfiiPtii
    .private_segment_fixed_size: 0
    .sgpr_count:     24
    .sgpr_spill_count: 0
    .symbol:         _Z8k_prep_wPKfiiPtii.kd
    .uniform_work_group_size: 1
    .uses_dynamic_stack: false
    .vgpr_count:     11
    .vgpr_spill_count: 0
    .wavefront_size: 64
; __global__ void k_prep_wup(const float* wuq, const float* wukv, bf16_t* out) {
;     const int idx = blockIdx.x * blockDim.x + threadIdx.x; if (idx >= NUP * KUP) return;
;     const int p = idx / KUP, k = idx % KUP; float v = 0.f;
;     if (p < 768) { if (k < 256) v = wuq[(size_t)k * 768 + wup_qcol(p)]; }
;     else { if (k >= 256) v = wukv[(size_t)(k - 256) * 1024 + (p - 768)]; }
;     out[idx] = f2bf(v);
; }
; __global__ void k_prep_gw(const float* ws, bf16_t* gw) {
;     const int idx = blockIdx.x * blockDim.x + threadIdx.x; if (idx >= DEPTH * NGRP * CHUNK * CHUNK) return;
;     const int s = idx & 127, t = (idx >> 7) & 127;
;     gw[idx] = (s <= t) ? f2bf(ws[idx]) : (bf16_t)0;
; }
; __global__ __launch_bounds__(512) void k_smallm(const float* in, int in_stride, int act, const float* W, int ldw, int N, int mode, const float* bias, float* out, int out_stride, int Nphys) {
;     __shared__ float sin_[1024 * 16];
;     __shared__ float red[8 * 64 * 16];
;     const int tid = threadIdx.x, lane = tid & 63, wave = tid >> 6;
;     for (int e = tid; e < 16 * 1024; e += 512) { const int b = e >> 10, k = e & 1023; float v = in[(size_t)b * in_stride + k]; if (act) v = v / (1.f + __expf(-v)); sin_[k * 16 + b] = v; }
;     __syncthreads();
;     const int p = blockIdx.x * 64 + lane; const int s = (p < Nphys) ? (mode == 1 ? win_src(p) : p) : -1; const bool ok = (s >= 0 && s < N);
;     float acc[16];
; #pragma unroll
;     for (int b = 0; b < 16; ++b) acc[b] = 0.f;
;     for (int k = wave * 128; k < wave * 128 + 128; ++k) {
;         const float w = ok ? W[(size_t)k * ldw + s] : 0.f;
;         const f32x4* sp = (const f32x4*)(sin_ + k * 16);
; #pragma unroll
;         for (int q = 0; q < 4; ++q) { const f32x4 v = sp[q]; acc[4 * q] += v[0] * w; acc[4 * q + 1] += v[1] * w; acc[4 * q + 2] += v[2] * w; acc[4 * q + 3] += v[3] * w; }
;     }
; #pragma unroll
;     for (int b = 0; b < 16; ++b) red[(wave * 64 + lane) * 16 + b] = acc[b];
;     __syncthreads();
;     for (int e = tid; e < 64 * 16; e += 512) { const int l = e >> 4, b = e & 15; float sum = 0.f;
; #pragma unroll
;         for (int w = 0; w < 8; ++w) sum += red[(w * 64 + l) * 16 + b];
;         const int pp = blockIdx.x * 64 + l; if (pp < Nphys) out[(size_t)b * out_stride + pp] = sum + (bias ? bias[pp] : 0.f); }
; }
  - .agpr_count:     0
    .args:
      - .address_space:  global
        .offset:         0
        .size:           8
        .value_kind:     global_buffer
      - .address_space:  global
        .offset:         8
        .size:           8
        .value_kind:     global_buffer
      - .address_space:  global
        .offset:         16
        .size:           8
        .value_kind:     global_buffer
      - .offset:         24
        .size:           4
        .value_kind:     hidden_block_count_x
      - .offset:         28
        .size:           4
        .value_kind:     hidden_block_count_y
      - .offset:         32
        .size:           4
        .value_kind:     hidden_block_count_z
      - .offset:         36
        .size:           2
        .value_kind:     hidden_group_size_x
      - .offset:         38
        .size:           2
        .value_kind:     hidden_group_size_y
      - .offset:         40
        .size:           2
        .value_kind:     hidden_group_size_z
      - .offset:         42
        .size:           2
        .value_kind:     hidden_remainder_x
      - .offset:         44
        .size:           2
        .value_kind:     hidden_remainder_y
      - .offset:         46
        .size:           2
        .value_kind:     hidden_remainder_z
      - .offset:         64
        .size:           8
        .value_kind:     hidden_global_offset_x
      - .offset:         72
        .size:           8
        .value_kind:     hidden_global_offset_y
      - .offset:         80
        .size:           8
        .value_kind:     hidden_global_offset_z
      - .offset:         88
        .size:           2
        .value_kind:     hidden_grid_dims
    .group_segment_fixed_size: 0
    .kernarg_segment_align: 8
    .kernarg_segment_size: 280
    .language:       OpenCL C
    .language_version:
      - 2
      - 0
    .max_flat_workgroup_size: 1024
    .name:           _Z10k_prep_wupPKfS0_Pt
    .private_segment_fixed_size: 0
    .sgpr_count:     16
    .sgpr_spill_count: 0
    .symbol:         _Z10k_prep_wupPKfS0_Pt.kd
    .uniform_work_group_size: 1
    .uses_dynamic_stack: false
    .vgpr_count:     8
    .vgpr_spill_count: 0
    .wavefront_size: 64
  - .agpr_count:     0
    .args:
      - .address_space:  global
        .offset:         0
        .size:           8
        .value_kind:     global_buffer
      - .address_space:  global
        .offset:         8
        .size:           8
        .value_kind:     global_buffer
      - .offset:         16
        .size:           4
        .value_kind:     hidden_block_count_x
      - .offset:         20
        .size:           4
        .value_kind:     hidden_block_count_y
      - .offset:         24
        .size:           4
        .value_kind:     hidden_block_count_z
      - .offset:         28
        .size:           2
        .value_kind:     hidden_group_size_x
      - .offset:         30
        .size:           2
        .value_kind:     hidden_group_size_y
      - .offset:         32
        .size:           2
        .value_kind:     hidden_group_size_z
      - .offset:         34
        .size:           2
        .value_kind:     hidden_remainder_x
      - .offset:         36
        .size:           2
        .value_kind:     hidden_remainder_y
      - .offset:         38
        .size:           2
        .value_kind:     hidden_remainder_z
      - .offset:         56
        .size:           8
        .value_kind:     hidden_global_offset_x
      - .offset:         64
        .size:           8
        .value_kind:     hidden_global_offset_y
      - .offset:         72
        .size:           8
        .value_kind:     hidden_global_offset_z
      - .offset:         80
        .size:           2
        .value_kind:     hidden_grid_dims
    .group_segment_fixed_size: 0
    .kernarg_segment_align: 8
    .kernarg_segment_size: 272
    .language:       OpenCL C
    .language_version:
      - 2
      - 0
    .max_flat_workgroup_size: 1024
    .name:           _Z9k_prep_gwPKfPt
    .private_segment_fixed_size: 0
    .sgpr_count:     12
    .sgpr_spill_count: 0
    .symbol:         _Z9k_prep_gwPKfPt.kd
    .uniform_work_group_size: 1
    .uses_dynamic_stack: false
    .vgpr_count:     6
    .vgpr_spill_count: 0
    .wavefront_size: 64
  - .agpr_count:     0
    .args:
      - .address_space:  global
        .offset:         0
        .size:           8
        .value_kind:     global_buffer
      - .offset:         8
        .size:           4
        .value_kind:     by_value
      - .offset:         12
        .size:           4
        .value_kind:     by_value
      - .address_space:  global
        .offset:         16
        .size:           8
        .value_kind:     global_buffer
      - .offset:         24
        .size:           4
        .value_kind:     by_value
      - .offset:         28
        .size:           4
        .value_kind:     by_value
      - .offset:         32
        .size:           4
        .value_kind:     by_value
      - .address_space:  global
        .offset:         40
        .size:           8
        .value_kind:     global_buffer
      - .address_space:  global
        .offset:         48
        .size:           8
        .value_kind:     global_buffer
      - .offset:         56
        .size:           4
        .value_kind:     by_value
      - .offset:         60
        .size:           4
        .value_kind:     by_value
    .group_segment_fixed_size: 98304
    .kernarg_segment_align: 8
    .kernarg_segment_size: 64
    .language:       OpenCL C
    .language_version:
      - 2
      - 0
    .max_flat_workgroup_size: 512
    .name:           _Z8k_smallmPKfiiS0_iiiS0_Pfii
    .private_segment_fixed_size: 0
    .sgpr_count:     20
    .sgpr_spill_count: 0
    .symbol:         _Z8k_smallmPKfiiS0_iiiS0_Pfii.kd
    .uniform_work_group_size: 1
    .uses_dynamic_stack: false
    .vgpr_count:     38
    .vgpr_spill_count: 0
    .wavefront_size: 64
; __global__ __launch_bounds__(256) void k_modx(const float* x, const float* g, const float* sc  , int sc_stride, bf16_t* A, float* ssq) {
;     const int row = blockIdx.x * 4 + (threadIdx.x >> 6), lane = threadIdx.x & 63; if (row >= T) return;
;     const int b = row / SEQ; const f32x4* xr = (const f32x4*)(x + (size_t)row * DM); float s = 0.f;
; #pragma unroll
;     for (int j = 0; j < 4; ++j) { const f32x4 v = xr[lane + 64 * j]; s += v[0] * v[0] + v[1] * v[1] + v[2] * v[2] + v[3] * v[3];
;         const int c = 4 * (lane + 64 * j); const f32x4 gv = *(const f32x4*)(g + c), sv = *(const f32x4*)(sc + (size_t)b * sc_stride + c);
;         unsigned lo = f2bf(v[0] * gv[0] * (1.f + sv[0])) | ((unsigned)f2bf(v[1] * gv[1] * (1.f + sv[1])) << 16);
;         unsigned hi = f2bf(v[2] * gv[2] * (1.f + sv[2])) | ((unsigned)f2bf(v[3] * gv[3] * (1.f + sv[3])) << 16);
;         *(uint2*)(A + (size_t)row * DM + c) = make_uint2(lo, hi); }
;     s = wave_sum(s);
;     if (lane < 16) ssq[(size_t)row * 16 + lane] = (lane == 0) ? s : 0.f;
; }
; __global__ __launch_bounds__(256) void k_final(const float* x, const float* g, float* out) {
;     const int row = blockIdx.x * 4 + (threadIdx.x >> 6), lane = threadIdx.x & 63; if (row >= T) return;
;     const f32x4* xr = (const f32x4*)(x + (size_t)row * DM); f32x4 v[4]; float s = 0.f;
; #pragma unroll
;     for (int j = 0; j < 4; ++j) { v[j] = xr[lane + 64 * j]; s += v[j][0] * v[j][0] + v[j][1] * v[j][1] + v[j][2] * v[j][2] + v[j][3] * v[j][3]; }
;     const float rstd = rsqrtf(wave_sum(s) * (1.f / DM) + EPS);
; #pragma unroll
;     for (int j = 0; j < 4; ++j) { const int c = 4 * (lane + 64 * j); const f32x4 gv = *(const f32x4*)(g + c); *(f32x4*)(out + (size_t)row * DM + c) = v[j] * rstd * gv; }
; }
; __global__ __launch_bounds__(256) void k_vn(const float* GV, bf16_t* VN) {
;     const int w = blockIdx.x * 4 + (threadIdx.x >> 6), lane = threadIdx.x & 63; if (w >= T * NGRP) return;
;     const int row = w >> 3, g = w & 7; const float v = GV[(size_t)row * 512 + g * 64 + lane];
;     const float mu = wave_sum(v) * (1.f / 64); const float d = v - mu; const float var = wave_sum(d * d) * (1.f / 64);
;     VN[(size_t)row * 512 + g * 64 + lane] = f2bf(d * rsqrtf(var + EPS));
; }
; __global__ __launch_bounds__(256) void k_lat(const float* ZL, const float* gq, const float* gkv, const float* rope, bf16_t* CQKV, float* ssqq, bf16_t* KR) {
  - .agpr_count:     0
    .args:
      - .address_space:  global
        .offset:         0
        .size:           8
        .value_kind:     global_buffer
      - .address_space:  global
        .offset:         8
        .size:           8
        .value_kind:     global_buffer
      - .address_space:  global
        .offset:         16
        .size:           8
        .value_kind:     global_buffer
      - .offset:         24
        .size:           4
        .value_kind:     by_value
      - .address_space:  global
        .offset:         32
        .size:           8
        .value_kind:     global_buffer
      - .address_space:  global
        .offset:         40
        .size:           8
        .value_kind:     global_buffer
    .group_segment_fixed_size: 0
    .kernarg_segment_align: 8
    .kernarg_segment_size: 48
    .language:       OpenCL C
    .language_version:
      - 2
      - 0
    .max_flat_workgroup_size: 256
    .name:           _Z6k_modxPKfS0_S0_iPtPf
    .private_segment_fixed_size: 0
    .sgpr_count:     19
    .sgpr_spill_count: 0
    .symbol:         _Z6k_modxPKfS0_S0_iPtPf.kd
    .uniform_work_group_size: 1
    .uses_dynamic_stack: false
    .vgpr_count:     40
    .vgpr_spill_count: 0
    .wavefront_size: 64
  - .agpr_count:     0
    .args:
      - .address_space:  global
        .offset:         0
        .size:           8
        .value_kind:     global_buffer
      - .address_space:  global
        .offset:         8
        .size:           8
        .value_kind:     global_buffer
      - .address_space:  global
        .offset:         16
        .size:           8
        .value_kind:     global_buffer
    .group_segment_fixed_size: 0
    .kernarg_segment_align: 8
    .kernarg_segment_size: 24
    .language:       OpenCL C
    .language_version:
      - 2
      - 0
    .max_flat_workgroup_size: 256
    .name:           _Z7k_finalPKfS0_Pf
    .private_segment_fixed_size: 0
    .sgpr_count:     14
    .sgpr_spill_count: 0
    .symbol:         _Z7k_finalPKfS0_Pf.kd
    .uniform_work_group_size: 1
    .uses_dynamic_stack: false
    .vgpr_count:     43
    .vgpr_spill_count: 0
    .wavefront_size: 64
  - .agpr_count:     0
    .args:
      - .address_space:  global
        .offset:         0
        .size:           8
        .value_kind:     global_buffer
      - .address_space:  global
        .offset:         8
        .size:           8
        .value_kind:     global_buffer
    .group_segment_fixed_size: 0
    .kernarg_segment_align: 8
    .kernarg_segment_size: 16
    .language:       OpenCL C
    .language_version:
      - 2
      - 0
    .max_flat_workgroup_size: 256
    .name:           _Z4k_vnPKfPt
    .private_segment_fixed_size: 0
    .sgpr_count:     10
    .sgpr_spill_count: 0
    .symbol:         _Z4k_vnPKfPt.kd
    .uniform_work_group_size: 1
    .uses_dynamic_stack: false
    .vgpr_count:     13
    .vgpr_spill_count: 0
    .wavefront_size: 64
  - .agpr_count:     0
    .args:
      - .address_space:  global
        .offset:         0
        .size:           8
        .value_kind:     global_buffer
      - .address_space:  global
        .offset:         8
        .size:           8
        .value_kind:     global_buffer
      - .address_space:  global
        .offset:         16
        .size:           8
        .value_kind:     global_buffer
      - .address_space:  global
        .offset:         24
        .size:           8
        .value_kind:     global_buffer
      - .address_space:  global
        .offset:         32
        .size:           8
        .value_kind:     global_buffer
      - .address_space:  global
        .offset:         40
        .size:           8
        .value_kind:     global_buffer
      - .address_space:  global
        .offset:         48
        .size:           8
        .value_kind:     global_buffer
    .group_segment_fixed_size: 0
    .kernarg_segment_align: 8
    .kernarg_segment_size: 56
    .language:       OpenCL C
    .language_version:
      - 2
      - 0
    .max_flat_workgroup_size: 256
    .name:           _Z5k_latPKfS0_S0_S0_PtPfS1_
    .private_segment_fixed_size: 0
    .sgpr_count:     26
    .sgpr_spill_count: 0
    .symbol:         _Z5k_latPKfS0_S0_S0_PtPfS1_.kd
    .uniform_work_group_size: 1
    .uses_dynamic_stack: false
    .vgpr_count:     32
    .vgpr_spill_count: 0
    .wavefront_size: 64
  - .agpr_count:     0
    .args:
      - .address_space:  global
        .offset:         0
        .size:           8
        .value_kind:     global_buffer
      - .address_space:  global
        .offset:         8
        .size:           8
        .value_kind:     global_buffer
      - .address_space:  global
        .offset:         16
        .size:           8
        .value_kind:     global_buffer
      - .offset:         24
        .size:           4
        .value_kind:     hidden_block_count_x
      - .offset:         28
        .size:           4
        .value_kind:     hidden_block_count_y
      - .offset:         32
        .size:           4
        .value_kind:     hidden_block_count_z
      - .offset:         36
        .size:           2
        .value_kind:     hidden_group_size_x
      - .offset:         38
        .size:           2
        .value_kind:     hidden_group_size_y
      - .offset:         40
        .size:           2
        .value_kind:     hidden_group_size_z
      - .offset:         42
        .size:           2
        .value_kind:     hidden_remainder_x
      - .offset:         44
        .size:           2
        .value_kind:     hidden_remainder_y
      - .offset:         46
        .size:           2
        .value_kind:     hidden_remainder_z
      - .offset:         64
        .size:           8
        .value_kind:     hidden_global_offset_x
      - .offset:         72
        .size:           8
        .value_kind:     hidden_global_offset_y
      - .offset:         80
        .size:           8
        .value_kind:     hidden_global_offset_z
      - .offset:         88
        .size:           2
        .value_kind:     hidden_grid_dims
    .group_segment_fixed_size: 0
    .kernarg_segment_align: 8
    .kernarg_segment_size: 280
    .language:       OpenCL C
    .language_version:
      - 2
      - 0
    .max_flat_workgroup_size: 1024
    .name:           _Z8k_rope_qPKfS0_Pt
    .private_segment_fixed_size: 0
    .sgpr_count:     14
    .sgpr_spill_count: 0
    .symbol:         _Z8k_rope_qPKfS0_Pt.kd
    .uniform_work_group_size: 1
    .uses_dynamic_stack: false
    .vgpr_count:     14
    .vgpr_spill_count: 0
    .wavefront_size: 64
; __global__ __launch_bounds__(512) void k_gmlp_naive(const bf16_t* U, const bf16_t* VN, const bf16_t* GW  , const float* bs  , const float* gog, bf16_t* Y, float* ssqy) {
;     const int row = blockIdx.x, g = threadIdx.x >> 6, d = threadIdx.x & 63, c = g * 64 + d;
;     const int tt = row & 127, t0 = row - tt;
;     const bf16_t* w = GW + ((size_t)g * CHUNK + tt) * CHUNK; float sum = 0.f;
;     for (int s = 0; s <= tt; ++s) sum += bf2f(w[s]) * bf2f(VN[(size_t)(t0 + s) * 512 + c]);
;     const float y = bf2f(U[(size_t)row * 512 + c]) * (sum + bs[g * CHUNK + tt]);
;     Y[(size_t)row * DM + c] = f2bf(y * gog[c]);
;     const float q = wave_sum(y * y); if (d == 0) ssqy[(size_t)row * 16 + g] = q;
; }
; __global__ __launch_bounds__(64) void k_attn_naive(const bf16_t* Q, const bf16_t* KN, const bf16_t* KR, const bf16_t* V, const float* goa, bf16_t* Y, float* ssqy) {
;     const int h = blockIdx.y, row = blockIdx.x * 64 + threadIdx.x, b = row / SEQ, i = row - b * SEQ;
;     const int iend = (blockIdx.x * 64 % SEQ) + 63;
;     float q[96];
; #pragma unroll
;     for (int d8 = 0; d8 < 12; ++d8) { const bf16x8 v = *(const bf16x8*)(Q + (size_t)row * 768 + h * 96 + d8 * 8);
; #pragma unroll
;         for (int j = 0; j < 8; ++j) q[d8 * 8 + j] = bf2f((bf16_t)v[j]); }
;     float o[64];
; #pragma unroll
;     for (int d = 0; d < 64; ++d) o[d] = 0.f;
;     float m = -1e30f, l = 0.f;
;     const size_t kb = (size_t)b * SEQ;
;     for (int j = 0; j <= iend; ++j) {
;         const bf16_t* kn = KN + (kb + j) * 512 + h * 64; const bf16_t* kr = KR + (kb + j) * 32; const bf16_t* vv = V + (kb + j) * 512 + h * 64;
;         float s = 0.f;
; #pragma unroll
;         for (int d8 = 0; d8 < 8; ++d8) { const bf16x8 kv = *(const bf16x8*)(kn + d8 * 8);
; #pragma unroll
;             for (int jj = 0; jj < 8; ++jj) s += q[d8 * 8 + jj] * bf2f((bf16_t)kv[jj]); }
; #pragma unroll
;         for (int d8 = 0; d8 < 4; ++d8) { const bf16x8 kv = *(const bf16x8*)(kr + d8 * 8);
; #pragma unroll
;             for (int jj = 0; jj < 8; ++jj) s += q[64 + d8 * 8 + jj] * bf2f((bf16_t)kv[jj]); }
;         if (j > i) s = -1e30f;
;         const float mn = fmaxf(m, s), alpha = exp2f(m - mn), p = (j > i) ? 0.f : exp2f(s - mn);
;         l = l * alpha + p; m = mn;
; #pragma unroll
;         for (int d8 = 0; d8 < 8; ++d8) { const bf16x8 v8 = *(const bf16x8*)(vv + d8 * 8);
; #pragma unroll
  - .agpr_count:     0
    .args:
      - .address_space:  global
        .offset:         0
        .size:           8
        .value_kind:     global_buffer
      - .address_space:  global
        .offset:         8
        .size:           8
        .value_kind:     global_buffer
      - .address_space:  global
        .offset:         16
        .size:           8
        .value_kind:     global_buffer
      - .address_space:  global
        .offset:         24
        .size:           8
        .value_kind:     global_buffer
      - .address_space:  global
        .offset:         32
        .size:           8
        .value_kind:     global_buffer
      - .address_space:  global
        .offset:         40
        .size:           8
        .value_kind:     global_buffer
      - .address_space:  global
        .offset:         48
        .size:           8
        .value_kind:     global_buffer
    .group_segment_fixed_size: 0
    .kernarg_segment_align: 8
    .kernarg_segment_size: 56
    .language:       OpenCL C
    .language_version:
      - 2
      - 0
    .max_flat_workgroup_size: 512
    .name:           _Z12k_gmlp_naivePKtS0_S0_PKfS2_PtPf
    .private_segment_fixed_size: 0
    .sgpr_count:     28
    .sgpr_spill_count: 0
    .symbol:         _Z12k_gmlp_naivePKtS0_S0_PKfS2_PtPf.kd
    .uniform_work_group_size: 1
    .uses_dynamic_stack: false
    .vgpr_count:     12
    .vgpr_spill_count: 0
    .wavefront_size: 64
  - .agpr_count:     0
    .args:
      - .address_space:  global
        .offset:         0
        .size:           8
        .value_kind:     global_buffer
      - .address_space:  global
        .offset:         8
        .size:           8
        .value_kind:     global_buffer
      - .address_space:  global
        .offset:         16
        .size:           8
        .value_kind:     global_buffer
      - .address_space:  global
        .offset:         24
        .size:           8
        .value_kind:     global_buffer
      - .address_space:  global
        .offset:         32
        .size:           8
        .value_kind:     global_buffer
      - .address_space:  global
        .offset:         40
        .size:           8
        .value_kind:     global_buffer
      - .address_space:  global
        .offset:         48
        .size:           8
        .value_kind:     global_buffer
    .group_segment_fixed_size: 0
    .kernarg_segment_align: 8
    .kernarg_segment_size: 56
    .language:       OpenCL C
    .language_version:
      - 2
      - 0
    .max_flat_workgroup_size: 64
    .name:           _Z12k_attn_naivePKtS0_S0_S0_PKfPtPf
    .private_segment_fixed_size: 0
    .sgpr_count:     28
    .sgpr_spill_count: 0
    .symbol:         _Z12k_attn_naivePKtS0_S0_S0_PKfPtPf.kd
    .uniform_work_group_size: 1
    .uses_dynamic_stack: false
    .vgpr_count:     184
    .vgpr_spill_count: 0
    .wavefront_size: 64
; __global__ void k_gm(const float* g  , const float* mod, int chunk, float* gmt) {
;     const int idx = blockIdx.x * blockDim.x + threadIdx.x; if (idx >= DEPTH * NB * DM) return;
;     const int c = idx & 1023, b = (idx >> 10) & 15, l = idx >> 14;
;     gmt[idx] = g[l * DM + c] * (1.f + mod[((size_t)l * NB + b) * NMOD + chunk * DM + c]);
; }
; __global__ void __launch_bounds__(NWAVES * 64, 2) mk_fwd(Args args) {
;     extern __shared__ __attribute__((aligned(16))) unsigned char lds[];
;     LAS unsigned char* L = (LAS unsigned char*)lds;
;     volatile LAS unsigned* MISC = (volatile LAS unsigned*)(L + MISC_OFF);
;     const int wid0 = __builtin_amdgcn_readfirstlane((int)threadIdx.x >> 6);
;     const int G = gridDim.x, bx = blockIdx.x;
;     { const int t0 = wid0 * 64 + lane_id(); for (int u = t0; u < (LDS_BYTES - LDSCTL_OFF) / 4; u += NWAVES * 64) ((LAS unsigned*)(L + LDSCTL_OFF))[u] = 0u; }
;     __syncthreads();
;     const int lo = __builtin_amdgcn_readfirstlane(args.ph_lo), hi = __builtin_amdgcn_readfirstlane(args.ph_hi);
;     unsigned* barw = (unsigned*)(args.ws + WS_CTL) + CW_BAR + __builtin_amdgcn_readfirstlane(args.li) * XCD_BAR_WORDS;
;     placement_init(barw, MISC + 8, wid0);
;     if (MK_IN_(PH_P0A)) { MK_STAMP(2 * (PH_P0A)); MK_PTRS(); MK_PLACE(); pro::phase0a(L, wid0, pl.jx * pl.nloc + pl.rank, G, args, zi, ws); }
;     MK_STAMP(2 * PH_P0A + 1); MK_SEAM(PH_P0A);
;     if (MK_IN_(PH_P0B)) { MK_STAMP(2 * (PH_P0B)); MK_PTRS(); MK_PLACE(); pro::phase0b(L, wid0, pl.jx * pl.nloc + pl.rank, G, args, zi, ws); }
;     MK_STAMP(2 * PH_P0B + 1); MK_SEAM(PH_P0B);
;     layer_phases<0>(args, L, MISC, wid0, lo, hi);
;     layer_phases<1>(args, L, MISC, wid0, lo, hi);
;     if (MK_IN_(PH_FINAL)) { MK_STAMP(2 * (PH_FINAL)); MK_PTRS(); MK_PLACE(); pro::phase_final(wid0, pl, INP(19), (const bf16_t*)out, out); }
;     MK_STAMP(2 * PH_FINAL + 1);
;     ...
;     if (bx == 0 && wid0 == 0 && lane_id() == 0) {
;         volatile LAS unsigned long long* st = (volatile LAS unsigned long long*)(L + LDSCTL_OFF + 1024); unsigned long long sel = 0;
;         if (PROBE_SEL >= 100) sel = st[PROBE_SEL - 60];
;         else if (PROBE_SEL >= 0) sel = st[2 * PROBE_SEL + 1] - st[2 * PROBE_SEL];
;         else { for (int k = 0; k < PH_FINAL; ++k) if (k != PH_L0 + 2 && k != PH_L0 + PH_PER_LAYER + 2) { int nx = k + 1; sel += st[2 * nx] - st[2 * k + 1]; } }
  - .agpr_count:     0
    .args:
      - .address_space:  global
        .offset:         0
        .size:           8
        .value_kind:     global_buffer
      - .address_space:  global
        .offset:         8
        .size:           8
        .value_kind:     global_buffer
      - .offset:         16
        .size:           4
        .value_kind:     by_value
      - .address_space:  global
        .offset:         24
        .size:           8
        .value_kind:     global_buffer
      - .offset:         32
        .size:           4
        .value_kind:     hidden_block_count_x
      - .offset:         36
        .size:           4
        .value_kind:     hidden_block_count_y
      - .offset:         40
        .size:           4
        .value_kind:     hidden_block_count_z
      - .offset:         44
        .size:           2
        .value_kind:     hidden_group_size_x
      - .offset:         46
        .size:           2
        .value_kind:     hidden_group_size_y
      - .offset:         48
        .size:           2
        .value_kind:     hidden_group_size_z
      - .offset:         50
        .size:           2
        .value_kind:     hidden_remainder_x
      - .offset:         52
        .size:           2
        .value_kind:     hidden_remainder_y
      - .offset:         54
        .size:           2
        .value_kind:     hidden_remainder_z
      - .offset:         72
        .size:           8
        .value_kind:     hidden_global_offset_x
      - .offset:         80
        .size:           8
        .value_kind:     hidden_global_offset_y
      - .offset:         88
        .size:           8
        .value_kind:     hidden_global_offset_z
      - .offset:         96
        .size:           2
        .value_kind:     hidden_grid_dims
    .group_segment_fixed_size: 0
    .kernarg_segment_align: 8
    .kernarg_segment_size: 288
    .language:       OpenCL C
    .language_version:
      - 2
      - 0
    .max_flat_workgroup_size: 1024
    .name:           _Z4k_gmPKfS0_iPf
    .private_segment_fixed_size: 0
    .sgpr_count:     14
    .sgpr_spill_count: 0
    .symbol:         _Z4k_gmPKfS0_iPf.kd
    .uniform_work_group_size: 1
    .uses_dynamic_stack: false
    .vgpr_count:     8
    .vgpr_spill_count: 0
    .wavefront_size: 64
  - .agpr_count:     0
    .args:
      - .offset:         0
        .size:           192
        .value_kind:     by_value
      - .offset:         192
        .size:           4
        .value_kind:     hidden_block_count_x
      - .offset:         196
        .size:           4
        .value_kind:     hidden_block_count_y
      - .offset:         200
        .size:           4
        .value_kind:     hidden_block_count_z
      - .offset:         204
        .size:           2
        .value_kind:     hidden_group_size_x
      - .offset:         206
        .size:           2
        .value_kind:     hidden_group_size_y
      - .offset:         208
        .size:           2
        .value_kind:     hidden_group_size_z
      - .offset:         210
        .size:           2
        .value_kind:     hidden_remainder_x
      - .offset:         212
        .size:           2
        .value_kind:     hidden_remainder_y
      - .offset:         214
        .size:           2
        .value_kind:     hidden_remainder_z
      - .offset:         232
        .size:           8
        .value_kind:     hidden_global_offset_x
      - .offset:         240
        .size:           8
        .value_kind:     hidden_global_offset_y
      - .offset:         248
        .size:           8
        .value_kind:     hidden_global_offset_z
      - .offset:         256
        .size:           2
        .value_kind:     hidden_grid_dims
      - .offset:         312
        .size:           4
        .value_kind:     hidden_dynamic_lds_size
    .group_segment_fixed_size: 0
    .kernarg_segment_align: 8
    .kernarg_segment_size: 448
    .language:       OpenCL C
    .language_version:
      - 2
      - 0
    .max_flat_workgroup_size: 512
    .name:           _Z6mk_fwd4Args
    .private_segment_fixed_size: 0
    .sgpr_count:     104
    .sgpr_spill_count: 119
    .symbol:         _Z6mk_fwd4Args.kd
    .uniform_work_group_size: 1
    .uses_dynamic_stack: false
    .vgpr_count:     256
    .vgpr_spill_count: 0
    .wavefront_size: 64
